# split packed f32 ops in attention loops into scalar pairs; hand-written lean P1 GEMM epilogue (SGPR-base addressing)
# speedup vs baseline: 1.0171x; 1.0171x over previous
.LBB0_134:
	s_lshr_b32 s5, s63, 2
	s_and_b32 s7, s63, 3
	s_cmp_gt_i32 s4, 15
	s_cbranch_scc1 .Lp1e_gates
	s_lshr_b32 s23, s4, 1
	s_lshl_b32 s30, s23, 24
	s_lshr_b32 s31, s6, 3
	s_lshl_b32 s31, s31, 21
	s_add_u32 s30, s30, s31
	s_and_b32 s31, s4, 1
	s_lshl_b32 s31, s31, 20
	s_add_u32 s30, s30, s31
	s_and_b32 s31, s6, 7
	s_lshl_b32 s31, s31, 8
	s_lshl_b32 s34, s5, 6
	s_add_u32 s31, s31, s34
	s_cmp_lt_u32 s23, 4
	s_cbranch_scc0 .Lp1e_dh128
	s_lshl_b32 s31, s31, 7
	s_add_u32 s30, s30, s31
	s_lshr_b32 s31, s7, 1
	s_lshl_b32 s31, s31, 18
	s_add_u32 s30, s30, s31
	s_and_b32 s31, s7, 1
	s_lshl_b32 s31, s31, 6
	s_add_u32 s30, s30, s31
	s_mov_b32 s34, 7
	s_branch .Lp1e_projc
.Lp1e_dh128:
	s_lshl_b32 s31, s31, 8
	s_add_u32 s30, s30, s31
	s_lshl_b32 s31, s7, 6
	s_add_u32 s30, s30, s31
	s_mov_b32 s34, 8
.Lp1e_projc:
	s_add_u32 s30, s78, s30
	s_addc_u32 s31, s79, 0
	s_mov_b32 s35, 0x80000
	v_and_b32_e32 v152, 15, v231
	v_lshrrev_b32_e32 v162, 4, v231
	v_lshlrev_b32_e32 v152, s34, v152
	s_lshl_b32 s23, 16, s34
	v_lshl_or_b32 v152, v162, 4, v152
	s_lshl_b32 s4, s23, 1
	s_add_u32 s6, s4, s23
	s_lshl_b32 s5, 0x80, s34
	v_add_u32_e32 v162, s23, v152
	v_add_u32_e32 v163, s4, v152
	v_add_u32_e32 v164, s6, v152
	v_cvt_pk_bf16_f32 v140, v140, v141
	v_cvt_pk_bf16_f32 v141, v142, v143
	v_cvt_pk_bf16_f32 v142, v136, v137
	v_cvt_pk_bf16_f32 v143, v138, v139
	global_store_dwordx4 v152, v[140:143], s[30:31]
	v_cvt_pk_bf16_f32 v124, v124, v125
	v_cvt_pk_bf16_f32 v125, v126, v127
	v_cvt_pk_bf16_f32 v126, v120, v121
	v_cvt_pk_bf16_f32 v127, v122, v123
	global_store_dwordx4 v162, v[124:127], s[30:31]
	v_cvt_pk_bf16_f32 v108, v108, v109
	v_cvt_pk_bf16_f32 v109, v110, v111
	v_cvt_pk_bf16_f32 v110, v104, v105
	v_cvt_pk_bf16_f32 v111, v106, v107
	global_store_dwordx4 v163, v[108:111], s[30:31]
	v_cvt_pk_bf16_f32 v84, v84, v85
	v_cvt_pk_bf16_f32 v85, v86, v87
	v_cvt_pk_bf16_f32 v86, v80, v81
	v_cvt_pk_bf16_f32 v87, v82, v83
	global_store_dwordx4 v164, v[84:87], s[30:31]
	s_add_u32 s30, s30, s35
	s_addc_u32 s31, s31, 0
	v_cvt_pk_bf16_f32 v132, v132, v133
	v_cvt_pk_bf16_f32 v133, v134, v135
	v_cvt_pk_bf16_f32 v134, v128, v129
	v_cvt_pk_bf16_f32 v135, v130, v131
	global_store_dwordx4 v152, v[132:135], s[30:31]
	v_cvt_pk_bf16_f32 v116, v116, v117
	v_cvt_pk_bf16_f32 v117, v118, v119
	v_cvt_pk_bf16_f32 v118, v112, v113
	v_cvt_pk_bf16_f32 v119, v114, v115
	global_store_dwordx4 v162, v[116:119], s[30:31]
	v_cvt_pk_bf16_f32 v100, v100, v101
	v_cvt_pk_bf16_f32 v101, v102, v103
	v_cvt_pk_bf16_f32 v102, v96, v97
	v_cvt_pk_bf16_f32 v103, v98, v99
	global_store_dwordx4 v163, v[100:103], s[30:31]
	v_cvt_pk_bf16_f32 v68, v68, v69
	v_cvt_pk_bf16_f32 v69, v70, v71
	v_cvt_pk_bf16_f32 v70, v64, v65
	v_cvt_pk_bf16_f32 v71, v66, v67
	global_store_dwordx4 v164, v[68:71], s[30:31]
	s_sub_u32 s30, s30, s35
	s_subb_u32 s31, s31, 0
	s_add_u32 s30, s30, s5
	s_addc_u32 s31, s31, 0
	v_cvt_pk_bf16_f32 v60, v60, v61
	v_cvt_pk_bf16_f32 v61, v62, v63
	v_cvt_pk_bf16_f32 v62, v56, v57
	v_cvt_pk_bf16_f32 v63, v58, v59
	global_store_dwordx4 v152, v[60:63], s[30:31]
	v_cvt_pk_bf16_f32 v44, v44, v45
	v_cvt_pk_bf16_f32 v45, v46, v47
	v_cvt_pk_bf16_f32 v46, v40, v41
	v_cvt_pk_bf16_f32 v47, v42, v43
	global_store_dwordx4 v162, v[44:47], s[30:31]
	v_cvt_pk_bf16_f32 v28, v28, v29
	v_cvt_pk_bf16_f32 v29, v30, v31
	v_cvt_pk_bf16_f32 v30, v24, v25
	v_cvt_pk_bf16_f32 v31, v26, v27
	global_store_dwordx4 v163, v[28:31], s[30:31]
	v_cvt_pk_bf16_f32 v12, v12, v13
	v_cvt_pk_bf16_f32 v13, v14, v15
	v_cvt_pk_bf16_f32 v14, v8, v9
	v_cvt_pk_bf16_f32 v15, v10, v11
	global_store_dwordx4 v164, v[12:15], s[30:31]
	s_add_u32 s30, s30, s35
	s_addc_u32 s31, s31, 0
	v_cvt_pk_bf16_f32 v52, v52, v53
	v_cvt_pk_bf16_f32 v53, v54, v55
	v_cvt_pk_bf16_f32 v54, v48, v49
	v_cvt_pk_bf16_f32 v55, v50, v51
	global_store_dwordx4 v152, v[52:55], s[30:31]
	v_cvt_pk_bf16_f32 v36, v36, v37
	v_cvt_pk_bf16_f32 v37, v38, v39
	v_cvt_pk_bf16_f32 v38, v32, v33
	v_cvt_pk_bf16_f32 v39, v34, v35
	global_store_dwordx4 v162, v[36:39], s[30:31]
	v_cvt_pk_bf16_f32 v20, v20, v21
	v_cvt_pk_bf16_f32 v21, v22, v23
	v_cvt_pk_bf16_f32 v22, v16, v17
	v_cvt_pk_bf16_f32 v23, v18, v19
	global_store_dwordx4 v163, v[20:23], s[30:31]
	v_cvt_pk_bf16_f32 v4, v4, v5
	v_cvt_pk_bf16_f32 v5, v6, v7
	v_cvt_pk_bf16_f32 v6, v0, v1
	v_cvt_pk_bf16_f32 v7, v2, v3
	global_store_dwordx4 v164, v[4:7], s[30:31]
	s_branch .Lp1e_done
.Lp1e_gates:
	s_lshl_b32 s30, s6, 8
	s_lshl_b32 s31, s5, 6
	s_add_u32 s30, s30, s31
	s_lshl_b32 s30, s30, 12
	s_sub_u32 s31, s4, 16
	s_lshl_b32 s31, s31, 9
	s_lshl_b32 s23, s7, 6
	s_add_u32 s31, s31, s23
	s_lshl_b32 s23, s31, 1
	s_add_u32 s23, s23, s53
	s_add_u32 s30, s30, s31
	v_lshrrev_b32_e32 v165, 4, v231
	s_add_u32 s30, s74, s30
	s_addc_u32 s31, s75, 0
	v_lshl_add_u32 v165, v165, 5, s23
	s_mov_b32 s34, 12
	s_mov_b32 s35, 0x100
	ds_read_b128 v[92:95], v165
	ds_read_b128 v[88:91], v165 offset:16
	ds_read_b128 v[76:79], v165 offset:512
	ds_read_b128 v[72:75], v165 offset:528
	v_and_b32_e32 v152, 15, v231
	v_lshrrev_b32_e32 v162, 4, v231
	v_lshlrev_b32_e32 v152, s34, v152
	s_lshl_b32 s23, 16, s34
	v_lshl_or_b32 v152, v162, 4, v152
	s_lshl_b32 s4, s23, 1
	s_add_u32 s6, s4, s23
	s_lshl_b32 s5, 0x80, s34
	v_add_u32_e32 v162, s23, v152
	v_add_u32_e32 v163, s4, v152
	v_add_u32_e32 v164, s6, v152
	s_waitcnt lgkmcnt(0)
	v_pk_add_f32 v[140:141], v[140:141], v[92:93]
	v_pk_add_f32 v[142:143], v[142:143], v[94:95]
	v_pk_add_f32 v[136:137], v[136:137], v[88:89]
	v_pk_add_f32 v[138:139], v[138:139], v[90:91]
	v_mul_f32_e32 v140, 0xbfb8aa3b, v140
	v_mul_f32_e32 v141, 0xbfb8aa3b, v141
	v_mul_f32_e32 v142, 0xbfb8aa3b, v142
	v_mul_f32_e32 v143, 0xbfb8aa3b, v143
	v_mul_f32_e32 v136, 0xbfb8aa3b, v136
	v_mul_f32_e32 v137, 0xbfb8aa3b, v137
	v_mul_f32_e32 v138, 0xbfb8aa3b, v138
	v_mul_f32_e32 v139, 0xbfb8aa3b, v139
	v_exp_f32_e32 v140, v140
	v_exp_f32_e32 v141, v141
	v_exp_f32_e32 v142, v142
	v_exp_f32_e32 v143, v143
	v_exp_f32_e32 v136, v136
	v_exp_f32_e32 v137, v137
	v_exp_f32_e32 v138, v138
	v_exp_f32_e32 v139, v139
	v_add_f32_e32 v140, 1.0, v140
	v_add_f32_e32 v141, 1.0, v141
	v_add_f32_e32 v142, 1.0, v142
	v_add_f32_e32 v143, 1.0, v143
	v_add_f32_e32 v136, 1.0, v136
	v_add_f32_e32 v137, 1.0, v137
	v_add_f32_e32 v138, 1.0, v138
	v_add_f32_e32 v139, 1.0, v139
	v_rcp_f32_e32 v140, v140
	v_rcp_f32_e32 v141, v141
	v_rcp_f32_e32 v142, v142
	v_rcp_f32_e32 v143, v143
	v_rcp_f32_e32 v136, v136
	v_rcp_f32_e32 v137, v137
	v_rcp_f32_e32 v138, v138
	v_rcp_f32_e32 v139, v139
	s_nop 0
	v_cvt_pk_bf16_f32 v140, v140, v141
	v_cvt_pk_bf16_f32 v141, v142, v143
	v_cvt_pk_bf16_f32 v142, v136, v137
	v_cvt_pk_bf16_f32 v143, v138, v139
	global_store_dwordx4 v152, v[140:143], s[30:31]
	v_pk_add_f32 v[124:125], v[124:125], v[92:93]
	v_pk_add_f32 v[126:127], v[126:127], v[94:95]
	v_pk_add_f32 v[120:121], v[120:121], v[88:89]
	v_pk_add_f32 v[122:123], v[122:123], v[90:91]
	v_mul_f32_e32 v124, 0xbfb8aa3b, v124
	v_mul_f32_e32 v125, 0xbfb8aa3b, v125
	v_mul_f32_e32 v126, 0xbfb8aa3b, v126
	v_mul_f32_e32 v127, 0xbfb8aa3b, v127
	v_mul_f32_e32 v120, 0xbfb8aa3b, v120
	v_mul_f32_e32 v121, 0xbfb8aa3b, v121
	v_mul_f32_e32 v122, 0xbfb8aa3b, v122
	v_mul_f32_e32 v123, 0xbfb8aa3b, v123
	v_exp_f32_e32 v124, v124
	v_exp_f32_e32 v125, v125
	v_exp_f32_e32 v126, v126
	v_exp_f32_e32 v127, v127
	v_exp_f32_e32 v120, v120
	v_exp_f32_e32 v121, v121
	v_exp_f32_e32 v122, v122
	v_exp_f32_e32 v123, v123
	v_add_f32_e32 v124, 1.0, v124
	v_add_f32_e32 v125, 1.0, v125
	v_add_f32_e32 v126, 1.0, v126
	v_add_f32_e32 v127, 1.0, v127
	v_add_f32_e32 v120, 1.0, v120
	v_add_f32_e32 v121, 1.0, v121
	v_add_f32_e32 v122, 1.0, v122
	v_add_f32_e32 v123, 1.0, v123
	v_rcp_f32_e32 v124, v124
	v_rcp_f32_e32 v125, v125
	v_rcp_f32_e32 v126, v126
	v_rcp_f32_e32 v127, v127
	v_rcp_f32_e32 v120, v120
	v_rcp_f32_e32 v121, v121
	v_rcp_f32_e32 v122, v122
	v_rcp_f32_e32 v123, v123
	s_nop 0
	v_cvt_pk_bf16_f32 v124, v124, v125
	v_cvt_pk_bf16_f32 v125, v126, v127
	v_cvt_pk_bf16_f32 v126, v120, v121
	v_cvt_pk_bf16_f32 v127, v122, v123
	global_store_dwordx4 v162, v[124:127], s[30:31]
	v_pk_add_f32 v[108:109], v[108:109], v[92:93]
	v_pk_add_f32 v[110:111], v[110:111], v[94:95]
	v_pk_add_f32 v[104:105], v[104:105], v[88:89]
	v_pk_add_f32 v[106:107], v[106:107], v[90:91]
	v_mul_f32_e32 v108, 0xbfb8aa3b, v108
	v_mul_f32_e32 v109, 0xbfb8aa3b, v109
	v_mul_f32_e32 v110, 0xbfb8aa3b, v110
	v_mul_f32_e32 v111, 0xbfb8aa3b, v111
	v_mul_f32_e32 v104, 0xbfb8aa3b, v104
	v_mul_f32_e32 v105, 0xbfb8aa3b, v105
	v_mul_f32_e32 v106, 0xbfb8aa3b, v106
	v_mul_f32_e32 v107, 0xbfb8aa3b, v107
	v_exp_f32_e32 v108, v108
	v_exp_f32_e32 v109, v109
	v_exp_f32_e32 v110, v110
	v_exp_f32_e32 v111, v111
	v_exp_f32_e32 v104, v104
	v_exp_f32_e32 v105, v105
	v_exp_f32_e32 v106, v106
	v_exp_f32_e32 v107, v107
	v_add_f32_e32 v108, 1.0, v108
	v_add_f32_e32 v109, 1.0, v109
	v_add_f32_e32 v110, 1.0, v110
	v_add_f32_e32 v111, 1.0, v111
	v_add_f32_e32 v104, 1.0, v104
	v_add_f32_e32 v105, 1.0, v105
	v_add_f32_e32 v106, 1.0, v106
	v_add_f32_e32 v107, 1.0, v107
	v_rcp_f32_e32 v108, v108
	v_rcp_f32_e32 v109, v109
	v_rcp_f32_e32 v110, v110
	v_rcp_f32_e32 v111, v111
	v_rcp_f32_e32 v104, v104
	v_rcp_f32_e32 v105, v105
	v_rcp_f32_e32 v106, v106
	v_rcp_f32_e32 v107, v107
	s_nop 0
	v_cvt_pk_bf16_f32 v108, v108, v109
	v_cvt_pk_bf16_f32 v109, v110, v111
	v_cvt_pk_bf16_f32 v110, v104, v105
	v_cvt_pk_bf16_f32 v111, v106, v107
	global_store_dwordx4 v163, v[108:111], s[30:31]
	v_pk_add_f32 v[84:85], v[84:85], v[92:93]
	v_pk_add_f32 v[86:87], v[86:87], v[94:95]
	v_pk_add_f32 v[80:81], v[80:81], v[88:89]
	v_pk_add_f32 v[82:83], v[82:83], v[90:91]
	v_mul_f32_e32 v84, 0xbfb8aa3b, v84
	v_mul_f32_e32 v85, 0xbfb8aa3b, v85
	v_mul_f32_e32 v86, 0xbfb8aa3b, v86
	v_mul_f32_e32 v87, 0xbfb8aa3b, v87
	v_mul_f32_e32 v80, 0xbfb8aa3b, v80
	v_mul_f32_e32 v81, 0xbfb8aa3b, v81
	v_mul_f32_e32 v82, 0xbfb8aa3b, v82
	v_mul_f32_e32 v83, 0xbfb8aa3b, v83
	v_exp_f32_e32 v84, v84
	v_exp_f32_e32 v85, v85
	v_exp_f32_e32 v86, v86
	v_exp_f32_e32 v87, v87
	v_exp_f32_e32 v80, v80
	v_exp_f32_e32 v81, v81
	v_exp_f32_e32 v82, v82
	v_exp_f32_e32 v83, v83
	v_add_f32_e32 v84, 1.0, v84
	v_add_f32_e32 v85, 1.0, v85
	v_add_f32_e32 v86, 1.0, v86
	v_add_f32_e32 v87, 1.0, v87
	v_add_f32_e32 v80, 1.0, v80
	v_add_f32_e32 v81, 1.0, v81
	v_add_f32_e32 v82, 1.0, v82
	v_add_f32_e32 v83, 1.0, v83
	v_rcp_f32_e32 v84, v84
	v_rcp_f32_e32 v85, v85
	v_rcp_f32_e32 v86, v86
	v_rcp_f32_e32 v87, v87
	v_rcp_f32_e32 v80, v80
	v_rcp_f32_e32 v81, v81
	v_rcp_f32_e32 v82, v82
	v_rcp_f32_e32 v83, v83
	s_nop 0
	v_cvt_pk_bf16_f32 v84, v84, v85
	v_cvt_pk_bf16_f32 v85, v86, v87
	v_cvt_pk_bf16_f32 v86, v80, v81
	v_cvt_pk_bf16_f32 v87, v82, v83
	global_store_dwordx4 v164, v[84:87], s[30:31]
	s_add_u32 s30, s30, s35
	s_addc_u32 s31, s31, 0
	v_pk_add_f32 v[132:133], v[132:133], v[76:77]
	v_pk_add_f32 v[134:135], v[134:135], v[78:79]
	v_pk_add_f32 v[128:129], v[128:129], v[72:73]
	v_pk_add_f32 v[130:131], v[130:131], v[74:75]
	v_mul_f32_e32 v132, 0xbfb8aa3b, v132
	v_mul_f32_e32 v133, 0xbfb8aa3b, v133
	v_mul_f32_e32 v134, 0xbfb8aa3b, v134
	v_mul_f32_e32 v135, 0xbfb8aa3b, v135
	v_mul_f32_e32 v128, 0xbfb8aa3b, v128
	v_mul_f32_e32 v129, 0xbfb8aa3b, v129
	v_mul_f32_e32 v130, 0xbfb8aa3b, v130
	v_mul_f32_e32 v131, 0xbfb8aa3b, v131
	v_exp_f32_e32 v132, v132
	v_exp_f32_e32 v133, v133
	v_exp_f32_e32 v134, v134
	v_exp_f32_e32 v135, v135
	v_exp_f32_e32 v128, v128
	v_exp_f32_e32 v129, v129
	v_exp_f32_e32 v130, v130
	v_exp_f32_e32 v131, v131
	v_add_f32_e32 v132, 1.0, v132
	v_add_f32_e32 v133, 1.0, v133
	v_add_f32_e32 v134, 1.0, v134
	v_add_f32_e32 v135, 1.0, v135
	v_add_f32_e32 v128, 1.0, v128
	v_add_f32_e32 v129, 1.0, v129
	v_add_f32_e32 v130, 1.0, v130
	v_add_f32_e32 v131, 1.0, v131
	v_rcp_f32_e32 v132, v132
	v_rcp_f32_e32 v133, v133
	v_rcp_f32_e32 v134, v134
	v_rcp_f32_e32 v135, v135
	v_rcp_f32_e32 v128, v128
	v_rcp_f32_e32 v129, v129
	v_rcp_f32_e32 v130, v130
	v_rcp_f32_e32 v131, v131
	s_nop 0
	v_cvt_pk_bf16_f32 v132, v132, v133
	v_cvt_pk_bf16_f32 v133, v134, v135
	v_cvt_pk_bf16_f32 v134, v128, v129
	v_cvt_pk_bf16_f32 v135, v130, v131
	global_store_dwordx4 v152, v[132:135], s[30:31]
	v_pk_add_f32 v[116:117], v[116:117], v[76:77]
	v_pk_add_f32 v[118:119], v[118:119], v[78:79]
	v_pk_add_f32 v[112:113], v[112:113], v[72:73]
	v_pk_add_f32 v[114:115], v[114:115], v[74:75]
	v_mul_f32_e32 v116, 0xbfb8aa3b, v116
	v_mul_f32_e32 v117, 0xbfb8aa3b, v117
	v_mul_f32_e32 v118, 0xbfb8aa3b, v118
	v_mul_f32_e32 v119, 0xbfb8aa3b, v119
	v_mul_f32_e32 v112, 0xbfb8aa3b, v112
	v_mul_f32_e32 v113, 0xbfb8aa3b, v113
	v_mul_f32_e32 v114, 0xbfb8aa3b, v114
	v_mul_f32_e32 v115, 0xbfb8aa3b, v115
	v_exp_f32_e32 v116, v116
	v_exp_f32_e32 v117, v117
	v_exp_f32_e32 v118, v118
	v_exp_f32_e32 v119, v119
	v_exp_f32_e32 v112, v112
	v_exp_f32_e32 v113, v113
	v_exp_f32_e32 v114, v114
	v_exp_f32_e32 v115, v115
	v_add_f32_e32 v116, 1.0, v116
	v_add_f32_e32 v117, 1.0, v117
	v_add_f32_e32 v118, 1.0, v118
	v_add_f32_e32 v119, 1.0, v119
	v_add_f32_e32 v112, 1.0, v112
	v_add_f32_e32 v113, 1.0, v113
	v_add_f32_e32 v114, 1.0, v114
	v_add_f32_e32 v115, 1.0, v115
	v_rcp_f32_e32 v116, v116
	v_rcp_f32_e32 v117, v117
	v_rcp_f32_e32 v118, v118
	v_rcp_f32_e32 v119, v119
	v_rcp_f32_e32 v112, v112
	v_rcp_f32_e32 v113, v113
	v_rcp_f32_e32 v114, v114
	v_rcp_f32_e32 v115, v115
	s_nop 0
	v_cvt_pk_bf16_f32 v116, v116, v117
	v_cvt_pk_bf16_f32 v117, v118, v119
	v_cvt_pk_bf16_f32 v118, v112, v113
	v_cvt_pk_bf16_f32 v119, v114, v115
	global_store_dwordx4 v162, v[116:119], s[30:31]
	v_pk_add_f32 v[100:101], v[100:101], v[76:77]
	v_pk_add_f32 v[102:103], v[102:103], v[78:79]
	v_pk_add_f32 v[96:97], v[96:97], v[72:73]
	v_pk_add_f32 v[98:99], v[98:99], v[74:75]
	v_mul_f32_e32 v100, 0xbfb8aa3b, v100
	v_mul_f32_e32 v101, 0xbfb8aa3b, v101
	v_mul_f32_e32 v102, 0xbfb8aa3b, v102
	v_mul_f32_e32 v103, 0xbfb8aa3b, v103
	v_mul_f32_e32 v96, 0xbfb8aa3b, v96
	v_mul_f32_e32 v97, 0xbfb8aa3b, v97
	v_mul_f32_e32 v98, 0xbfb8aa3b, v98
	v_mul_f32_e32 v99, 0xbfb8aa3b, v99
	v_exp_f32_e32 v100, v100
	v_exp_f32_e32 v101, v101
	v_exp_f32_e32 v102, v102
	v_exp_f32_e32 v103, v103
	v_exp_f32_e32 v96, v96
	v_exp_f32_e32 v97, v97
	v_exp_f32_e32 v98, v98
	v_exp_f32_e32 v99, v99
	v_add_f32_e32 v100, 1.0, v100
	v_add_f32_e32 v101, 1.0, v101
	v_add_f32_e32 v102, 1.0, v102
	v_add_f32_e32 v103, 1.0, v103
	v_add_f32_e32 v96, 1.0, v96
	v_add_f32_e32 v97, 1.0, v97
	v_add_f32_e32 v98, 1.0, v98
	v_add_f32_e32 v99, 1.0, v99
	v_rcp_f32_e32 v100, v100
	v_rcp_f32_e32 v101, v101
	v_rcp_f32_e32 v102, v102
	v_rcp_f32_e32 v103, v103
	v_rcp_f32_e32 v96, v96
	v_rcp_f32_e32 v97, v97
	v_rcp_f32_e32 v98, v98
	v_rcp_f32_e32 v99, v99
	s_nop 0
	v_cvt_pk_bf16_f32 v100, v100, v101
	v_cvt_pk_bf16_f32 v101, v102, v103
	v_cvt_pk_bf16_f32 v102, v96, v97
	v_cvt_pk_bf16_f32 v103, v98, v99
	global_store_dwordx4 v163, v[100:103], s[30:31]
	v_pk_add_f32 v[68:69], v[68:69], v[76:77]
	v_pk_add_f32 v[70:71], v[70:71], v[78:79]
	v_pk_add_f32 v[64:65], v[64:65], v[72:73]
	v_pk_add_f32 v[66:67], v[66:67], v[74:75]
	v_mul_f32_e32 v68, 0xbfb8aa3b, v68
	v_mul_f32_e32 v69, 0xbfb8aa3b, v69
	v_mul_f32_e32 v70, 0xbfb8aa3b, v70
	v_mul_f32_e32 v71, 0xbfb8aa3b, v71
	v_mul_f32_e32 v64, 0xbfb8aa3b, v64
	v_mul_f32_e32 v65, 0xbfb8aa3b, v65
	v_mul_f32_e32 v66, 0xbfb8aa3b, v66
	v_mul_f32_e32 v67, 0xbfb8aa3b, v67
	v_exp_f32_e32 v68, v68
	v_exp_f32_e32 v69, v69
	v_exp_f32_e32 v70, v70
	v_exp_f32_e32 v71, v71
	v_exp_f32_e32 v64, v64
	v_exp_f32_e32 v65, v65
	v_exp_f32_e32 v66, v66
	v_exp_f32_e32 v67, v67
	v_add_f32_e32 v68, 1.0, v68
	v_add_f32_e32 v69, 1.0, v69
	v_add_f32_e32 v70, 1.0, v70
	v_add_f32_e32 v71, 1.0, v71
	v_add_f32_e32 v64, 1.0, v64
	v_add_f32_e32 v65, 1.0, v65
	v_add_f32_e32 v66, 1.0, v66
	v_add_f32_e32 v67, 1.0, v67
	v_rcp_f32_e32 v68, v68
	v_rcp_f32_e32 v69, v69
	v_rcp_f32_e32 v70, v70
	v_rcp_f32_e32 v71, v71
	v_rcp_f32_e32 v64, v64
	v_rcp_f32_e32 v65, v65
	v_rcp_f32_e32 v66, v66
	v_rcp_f32_e32 v67, v67
	s_nop 0
	v_cvt_pk_bf16_f32 v68, v68, v69
	v_cvt_pk_bf16_f32 v69, v70, v71
	v_cvt_pk_bf16_f32 v70, v64, v65
	v_cvt_pk_bf16_f32 v71, v66, v67
	global_store_dwordx4 v164, v[68:71], s[30:31]
	s_sub_u32 s30, s30, s35
	s_subb_u32 s31, s31, 0
	s_add_u32 s30, s30, s5
	s_addc_u32 s31, s31, 0
	v_pk_add_f32 v[60:61], v[60:61], v[92:93]
	v_pk_add_f32 v[62:63], v[62:63], v[94:95]
	v_pk_add_f32 v[56:57], v[56:57], v[88:89]
	v_pk_add_f32 v[58:59], v[58:59], v[90:91]
	v_mul_f32_e32 v60, 0xbfb8aa3b, v60
	v_mul_f32_e32 v61, 0xbfb8aa3b, v61
	v_mul_f32_e32 v62, 0xbfb8aa3b, v62
	v_mul_f32_e32 v63, 0xbfb8aa3b, v63
	v_mul_f32_e32 v56, 0xbfb8aa3b, v56
	v_mul_f32_e32 v57, 0xbfb8aa3b, v57
	v_mul_f32_e32 v58, 0xbfb8aa3b, v58
	v_mul_f32_e32 v59, 0xbfb8aa3b, v59
	v_exp_f32_e32 v60, v60
	v_exp_f32_e32 v61, v61
	v_exp_f32_e32 v62, v62
	v_exp_f32_e32 v63, v63
	v_exp_f32_e32 v56, v56
	v_exp_f32_e32 v57, v57
	v_exp_f32_e32 v58, v58
	v_exp_f32_e32 v59, v59
	v_add_f32_e32 v60, 1.0, v60
	v_add_f32_e32 v61, 1.0, v61
	v_add_f32_e32 v62, 1.0, v62
	v_add_f32_e32 v63, 1.0, v63
	v_add_f32_e32 v56, 1.0, v56
	v_add_f32_e32 v57, 1.0, v57
	v_add_f32_e32 v58, 1.0, v58
	v_add_f32_e32 v59, 1.0, v59
	v_rcp_f32_e32 v60, v60
	v_rcp_f32_e32 v61, v61
	v_rcp_f32_e32 v62, v62
	v_rcp_f32_e32 v63, v63
	v_rcp_f32_e32 v56, v56
	v_rcp_f32_e32 v57, v57
	v_rcp_f32_e32 v58, v58
	v_rcp_f32_e32 v59, v59
	s_nop 0
	v_cvt_pk_bf16_f32 v60, v60, v61
	v_cvt_pk_bf16_f32 v61, v62, v63
	v_cvt_pk_bf16_f32 v62, v56, v57
	v_cvt_pk_bf16_f32 v63, v58, v59
	global_store_dwordx4 v152, v[60:63], s[30:31]
	v_pk_add_f32 v[44:45], v[44:45], v[92:93]
	v_pk_add_f32 v[46:47], v[46:47], v[94:95]
	v_pk_add_f32 v[40:41], v[40:41], v[88:89]
	v_pk_add_f32 v[42:43], v[42:43], v[90:91]
	v_mul_f32_e32 v44, 0xbfb8aa3b, v44
	v_mul_f32_e32 v45, 0xbfb8aa3b, v45
	v_mul_f32_e32 v46, 0xbfb8aa3b, v46
	v_mul_f32_e32 v47, 0xbfb8aa3b, v47
	v_mul_f32_e32 v40, 0xbfb8aa3b, v40
	v_mul_f32_e32 v41, 0xbfb8aa3b, v41
	v_mul_f32_e32 v42, 0xbfb8aa3b, v42
	v_mul_f32_e32 v43, 0xbfb8aa3b, v43
	v_exp_f32_e32 v44, v44
	v_exp_f32_e32 v45, v45
	v_exp_f32_e32 v46, v46
	v_exp_f32_e32 v47, v47
	v_exp_f32_e32 v40, v40
	v_exp_f32_e32 v41, v41
	v_exp_f32_e32 v42, v42
	v_exp_f32_e32 v43, v43
	v_add_f32_e32 v44, 1.0, v44
	v_add_f32_e32 v45, 1.0, v45
	v_add_f32_e32 v46, 1.0, v46
	v_add_f32_e32 v47, 1.0, v47
	v_add_f32_e32 v40, 1.0, v40
	v_add_f32_e32 v41, 1.0, v41
	v_add_f32_e32 v42, 1.0, v42
	v_add_f32_e32 v43, 1.0, v43
	v_rcp_f32_e32 v44, v44
	v_rcp_f32_e32 v45, v45
	v_rcp_f32_e32 v46, v46
	v_rcp_f32_e32 v47, v47
	v_rcp_f32_e32 v40, v40
	v_rcp_f32_e32 v41, v41
	v_rcp_f32_e32 v42, v42
	v_rcp_f32_e32 v43, v43
	s_nop 0
	v_cvt_pk_bf16_f32 v44, v44, v45
	v_cvt_pk_bf16_f32 v45, v46, v47
	v_cvt_pk_bf16_f32 v46, v40, v41
	v_cvt_pk_bf16_f32 v47, v42, v43
	global_store_dwordx4 v162, v[44:47], s[30:31]
	v_pk_add_f32 v[28:29], v[28:29], v[92:93]
	v_pk_add_f32 v[30:31], v[30:31], v[94:95]
	v_pk_add_f32 v[24:25], v[24:25], v[88:89]
	v_pk_add_f32 v[26:27], v[26:27], v[90:91]
	v_mul_f32_e32 v28, 0xbfb8aa3b, v28
	v_mul_f32_e32 v29, 0xbfb8aa3b, v29
	v_mul_f32_e32 v30, 0xbfb8aa3b, v30
	v_mul_f32_e32 v31, 0xbfb8aa3b, v31
	v_mul_f32_e32 v24, 0xbfb8aa3b, v24
	v_mul_f32_e32 v25, 0xbfb8aa3b, v25
	v_mul_f32_e32 v26, 0xbfb8aa3b, v26
	v_mul_f32_e32 v27, 0xbfb8aa3b, v27
	v_exp_f32_e32 v28, v28
	v_exp_f32_e32 v29, v29
	v_exp_f32_e32 v30, v30
	v_exp_f32_e32 v31, v31
	v_exp_f32_e32 v24, v24
	v_exp_f32_e32 v25, v25
	v_exp_f32_e32 v26, v26
	v_exp_f32_e32 v27, v27
	v_add_f32_e32 v28, 1.0, v28
	v_add_f32_e32 v29, 1.0, v29
	v_add_f32_e32 v30, 1.0, v30
	v_add_f32_e32 v31, 1.0, v31
	v_add_f32_e32 v24, 1.0, v24
	v_add_f32_e32 v25, 1.0, v25
	v_add_f32_e32 v26, 1.0, v26
	v_add_f32_e32 v27, 1.0, v27
	v_rcp_f32_e32 v28, v28
	v_rcp_f32_e32 v29, v29
	v_rcp_f32_e32 v30, v30
	v_rcp_f32_e32 v31, v31
	v_rcp_f32_e32 v24, v24
	v_rcp_f32_e32 v25, v25
	v_rcp_f32_e32 v26, v26
	v_rcp_f32_e32 v27, v27
	s_nop 0
	v_cvt_pk_bf16_f32 v28, v28, v29
	v_cvt_pk_bf16_f32 v29, v30, v31
	v_cvt_pk_bf16_f32 v30, v24, v25
	v_cvt_pk_bf16_f32 v31, v26, v27
	global_store_dwordx4 v163, v[28:31], s[30:31]
	v_pk_add_f32 v[12:13], v[12:13], v[92:93]
	v_pk_add_f32 v[14:15], v[14:15], v[94:95]
	v_pk_add_f32 v[8:9], v[8:9], v[88:89]
	v_pk_add_f32 v[10:11], v[10:11], v[90:91]
	v_mul_f32_e32 v12, 0xbfb8aa3b, v12
	v_mul_f32_e32 v13, 0xbfb8aa3b, v13
	v_mul_f32_e32 v14, 0xbfb8aa3b, v14
	v_mul_f32_e32 v15, 0xbfb8aa3b, v15
	v_mul_f32_e32 v8, 0xbfb8aa3b, v8
	v_mul_f32_e32 v9, 0xbfb8aa3b, v9
	v_mul_f32_e32 v10, 0xbfb8aa3b, v10
	v_mul_f32_e32 v11, 0xbfb8aa3b, v11
	v_exp_f32_e32 v12, v12
	v_exp_f32_e32 v13, v13
	v_exp_f32_e32 v14, v14
	v_exp_f32_e32 v15, v15
	v_exp_f32_e32 v8, v8
	v_exp_f32_e32 v9, v9
	v_exp_f32_e32 v10, v10
	v_exp_f32_e32 v11, v11
	v_add_f32_e32 v12, 1.0, v12
	v_add_f32_e32 v13, 1.0, v13
	v_add_f32_e32 v14, 1.0, v14
	v_add_f32_e32 v15, 1.0, v15
	v_add_f32_e32 v8, 1.0, v8
	v_add_f32_e32 v9, 1.0, v9
	v_add_f32_e32 v10, 1.0, v10
	v_add_f32_e32 v11, 1.0, v11
	v_rcp_f32_e32 v12, v12
	v_rcp_f32_e32 v13, v13
	v_rcp_f32_e32 v14, v14
	v_rcp_f32_e32 v15, v15
	v_rcp_f32_e32 v8, v8
	v_rcp_f32_e32 v9, v9
	v_rcp_f32_e32 v10, v10
	v_rcp_f32_e32 v11, v11
	s_nop 0
	v_cvt_pk_bf16_f32 v12, v12, v13
	v_cvt_pk_bf16_f32 v13, v14, v15
	v_cvt_pk_bf16_f32 v14, v8, v9
	v_cvt_pk_bf16_f32 v15, v10, v11
	global_store_dwordx4 v164, v[12:15], s[30:31]
	s_add_u32 s30, s30, s35
	s_addc_u32 s31, s31, 0
	v_pk_add_f32 v[52:53], v[52:53], v[76:77]
	v_pk_add_f32 v[54:55], v[54:55], v[78:79]
	v_pk_add_f32 v[48:49], v[48:49], v[72:73]
	v_pk_add_f32 v[50:51], v[50:51], v[74:75]
	v_mul_f32_e32 v52, 0xbfb8aa3b, v52
	v_mul_f32_e32 v53, 0xbfb8aa3b, v53
	v_mul_f32_e32 v54, 0xbfb8aa3b, v54
	v_mul_f32_e32 v55, 0xbfb8aa3b, v55
	v_mul_f32_e32 v48, 0xbfb8aa3b, v48
	v_mul_f32_e32 v49, 0xbfb8aa3b, v49
	v_mul_f32_e32 v50, 0xbfb8aa3b, v50
	v_mul_f32_e32 v51, 0xbfb8aa3b, v51
	v_exp_f32_e32 v52, v52
	v_exp_f32_e32 v53, v53
	v_exp_f32_e32 v54, v54
	v_exp_f32_e32 v55, v55
	v_exp_f32_e32 v48, v48
	v_exp_f32_e32 v49, v49
	v_exp_f32_e32 v50, v50
	v_exp_f32_e32 v51, v51
	v_add_f32_e32 v52, 1.0, v52
	v_add_f32_e32 v53, 1.0, v53
	v_add_f32_e32 v54, 1.0, v54
	v_add_f32_e32 v55, 1.0, v55
	v_add_f32_e32 v48, 1.0, v48
	v_add_f32_e32 v49, 1.0, v49
	v_add_f32_e32 v50, 1.0, v50
	v_add_f32_e32 v51, 1.0, v51
	v_rcp_f32_e32 v52, v52
	v_rcp_f32_e32 v53, v53
	v_rcp_f32_e32 v54, v54
	v_rcp_f32_e32 v55, v55
	v_rcp_f32_e32 v48, v48
	v_rcp_f32_e32 v49, v49
	v_rcp_f32_e32 v50, v50
	v_rcp_f32_e32 v51, v51
	s_nop 0
	v_cvt_pk_bf16_f32 v52, v52, v53
	v_cvt_pk_bf16_f32 v53, v54, v55
	v_cvt_pk_bf16_f32 v54, v48, v49
	v_cvt_pk_bf16_f32 v55, v50, v51
	global_store_dwordx4 v152, v[52:55], s[30:31]
	v_pk_add_f32 v[36:37], v[36:37], v[76:77]
	v_pk_add_f32 v[38:39], v[38:39], v[78:79]
	v_pk_add_f32 v[32:33], v[32:33], v[72:73]
	v_pk_add_f32 v[34:35], v[34:35], v[74:75]
	v_mul_f32_e32 v36, 0xbfb8aa3b, v36
	v_mul_f32_e32 v37, 0xbfb8aa3b, v37
	v_mul_f32_e32 v38, 0xbfb8aa3b, v38
	v_mul_f32_e32 v39, 0xbfb8aa3b, v39
	v_mul_f32_e32 v32, 0xbfb8aa3b, v32
	v_mul_f32_e32 v33, 0xbfb8aa3b, v33
	v_mul_f32_e32 v34, 0xbfb8aa3b, v34
	v_mul_f32_e32 v35, 0xbfb8aa3b, v35
	v_exp_f32_e32 v36, v36
	v_exp_f32_e32 v37, v37
	v_exp_f32_e32 v38, v38
	v_exp_f32_e32 v39, v39
	v_exp_f32_e32 v32, v32
	v_exp_f32_e32 v33, v33
	v_exp_f32_e32 v34, v34
	v_exp_f32_e32 v35, v35
	v_add_f32_e32 v36, 1.0, v36
	v_add_f32_e32 v37, 1.0, v37
	v_add_f32_e32 v38, 1.0, v38
	v_add_f32_e32 v39, 1.0, v39
	v_add_f32_e32 v32, 1.0, v32
	v_add_f32_e32 v33, 1.0, v33
	v_add_f32_e32 v34, 1.0, v34
	v_add_f32_e32 v35, 1.0, v35
	v_rcp_f32_e32 v36, v36
	v_rcp_f32_e32 v37, v37
	v_rcp_f32_e32 v38, v38
	v_rcp_f32_e32 v39, v39
	v_rcp_f32_e32 v32, v32
	v_rcp_f32_e32 v33, v33
	v_rcp_f32_e32 v34, v34
	v_rcp_f32_e32 v35, v35
	s_nop 0
	v_cvt_pk_bf16_f32 v36, v36, v37
	v_cvt_pk_bf16_f32 v37, v38, v39
	v_cvt_pk_bf16_f32 v38, v32, v33
	v_cvt_pk_bf16_f32 v39, v34, v35
	global_store_dwordx4 v162, v[36:39], s[30:31]
	v_pk_add_f32 v[20:21], v[20:21], v[76:77]
	v_pk_add_f32 v[22:23], v[22:23], v[78:79]
	v_pk_add_f32 v[16:17], v[16:17], v[72:73]
	v_pk_add_f32 v[18:19], v[18:19], v[74:75]
	v_mul_f32_e32 v20, 0xbfb8aa3b, v20
	v_mul_f32_e32 v21, 0xbfb8aa3b, v21
	v_mul_f32_e32 v22, 0xbfb8aa3b, v22
	v_mul_f32_e32 v23, 0xbfb8aa3b, v23
	v_mul_f32_e32 v16, 0xbfb8aa3b, v16
	v_mul_f32_e32 v17, 0xbfb8aa3b, v17
	v_mul_f32_e32 v18, 0xbfb8aa3b, v18
	v_mul_f32_e32 v19, 0xbfb8aa3b, v19
	v_exp_f32_e32 v20, v20
	v_exp_f32_e32 v21, v21
	v_exp_f32_e32 v22, v22
	v_exp_f32_e32 v23, v23
	v_exp_f32_e32 v16, v16
	v_exp_f32_e32 v17, v17
	v_exp_f32_e32 v18, v18
	v_exp_f32_e32 v19, v19
	v_add_f32_e32 v20, 1.0, v20
	v_add_f32_e32 v21, 1.0, v21
	v_add_f32_e32 v22, 1.0, v22
	v_add_f32_e32 v23, 1.0, v23
	v_add_f32_e32 v16, 1.0, v16
	v_add_f32_e32 v17, 1.0, v17
	v_add_f32_e32 v18, 1.0, v18
	v_add_f32_e32 v19, 1.0, v19
	v_rcp_f32_e32 v20, v20
	v_rcp_f32_e32 v21, v21
	v_rcp_f32_e32 v22, v22
	v_rcp_f32_e32 v23, v23
	v_rcp_f32_e32 v16, v16
	v_rcp_f32_e32 v17, v17
	v_rcp_f32_e32 v18, v18
	v_rcp_f32_e32 v19, v19
	s_nop 0
	v_cvt_pk_bf16_f32 v20, v20, v21
	v_cvt_pk_bf16_f32 v21, v22, v23
	v_cvt_pk_bf16_f32 v22, v16, v17
	v_cvt_pk_bf16_f32 v23, v18, v19
	global_store_dwordx4 v163, v[20:23], s[30:31]
	v_pk_add_f32 v[4:5], v[4:5], v[76:77]
	v_pk_add_f32 v[6:7], v[6:7], v[78:79]
	v_pk_add_f32 v[0:1], v[0:1], v[72:73]
	v_pk_add_f32 v[2:3], v[2:3], v[74:75]
	v_mul_f32_e32 v4, 0xbfb8aa3b, v4
	v_mul_f32_e32 v5, 0xbfb8aa3b, v5
	v_mul_f32_e32 v6, 0xbfb8aa3b, v6
	v_mul_f32_e32 v7, 0xbfb8aa3b, v7
	v_mul_f32_e32 v0, 0xbfb8aa3b, v0
	v_mul_f32_e32 v1, 0xbfb8aa3b, v1
	v_mul_f32_e32 v2, 0xbfb8aa3b, v2
	v_mul_f32_e32 v3, 0xbfb8aa3b, v3
	v_exp_f32_e32 v4, v4
	v_exp_f32_e32 v5, v5
	v_exp_f32_e32 v6, v6
	v_exp_f32_e32 v7, v7
	v_exp_f32_e32 v0, v0
	v_exp_f32_e32 v1, v1
	v_exp_f32_e32 v2, v2
	v_exp_f32_e32 v3, v3
	v_add_f32_e32 v4, 1.0, v4
	v_add_f32_e32 v5, 1.0, v5
	v_add_f32_e32 v6, 1.0, v6
	v_add_f32_e32 v7, 1.0, v7
	v_add_f32_e32 v0, 1.0, v0
	v_add_f32_e32 v1, 1.0, v1
	v_add_f32_e32 v2, 1.0, v2
	v_add_f32_e32 v3, 1.0, v3
	v_rcp_f32_e32 v4, v4
	v_rcp_f32_e32 v5, v5
	v_rcp_f32_e32 v6, v6
	v_rcp_f32_e32 v7, v7
	v_rcp_f32_e32 v0, v0
	v_rcp_f32_e32 v1, v1
	v_rcp_f32_e32 v2, v2
	v_rcp_f32_e32 v3, v3
	s_nop 0
	v_cvt_pk_bf16_f32 v4, v4, v5
	v_cvt_pk_bf16_f32 v5, v6, v7
	v_cvt_pk_bf16_f32 v6, v0, v1
	v_cvt_pk_bf16_f32 v7, v2, v3
	global_store_dwordx4 v164, v[4:7], s[30:31]
.Lp1e_done:
	s_andn2_b64 vcc, exec, s[8:9]
	s_mov_b64 s[4:5], -1
	s_cbranch_vccnz .LBB0_116
.LBB0_239:
	s_andn2_b64 vcc, exec, s[16:17]
	s_cbranch_vccnz .LBB0_115
	s_barrier
	s_branch .LBB0_115

.LBB0_347:
	v_mul_f32_e32 v18, 0x3e38aa3b, v18
	v_exp_f32_e32 v18, v18
	s_nop 7
	v_mul_f32_e32 v2, 0x3e38aa3b, v2
	v_exp_f32_e32 v2, v2
	v_mul_f32_e32 v3, 0x3e38aa3b, v3
	v_add_f32_e32 v18, 1.0, v18
	v_exp_f32_e32 v3, v3
	v_add_f32_e32 v66, 1.0, v2
	v_rcp_f32_e32 v2, v18
	v_mul_f32_e32 v18, 0x3e38aa3b, v19
	v_mul_f32_e32 v19, 0x3e38aa3b, v20
	v_exp_f32_e32 v19, v19
	v_add_f32_e32 v3, 1.0, v3
	v_mul_f32_e32 v4, 0x3e38aa3b, v4
	v_exp_f32_e32 v4, v4
	v_rcp_f32_e32 v20, v3
	v_add_f32_e32 v3, 1.0, v19
	v_mul_f32_e32 v19, 0x3e38aa3b, v21
	v_exp_f32_e32 v19, v19
	v_mul_f32_e32 v5, 0x3e38aa3b, v5
	v_exp_f32_e32 v5, v5
	v_add_f32_e32 v4, 1.0, v4
	v_rcp_f32_e32 v67, v4
	v_add_f32_e32 v4, 1.0, v19
	v_rcp_f32_e32 v19, v4
	v_add_f32_e32 v4, 1.0, v5
	v_mul_f32_e32 v5, 0x3e38aa3b, v22
	v_mul_f32_e32 v6, 0x3e38aa3b, v6
	v_exp_f32_e32 v5, v5
	v_exp_f32_e32 v6, v6
	v_rcp_f32_e32 v21, v4
	v_mul_f32_e32 v7, 0x3e38aa3b, v7
	v_add_f32_e32 v4, 1.0, v5
	v_add_f32_e32 v5, 1.0, v6
	v_mul_f32_e32 v6, 0x3e38aa3b, v23
	v_exp_f32_e32 v6, v6
	v_exp_f32_e32 v7, v7
	v_rcp_f32_e32 v22, v5
	v_mul_f32_e32 v8, 0x3e38aa3b, v8
	v_add_f32_e32 v5, 1.0, v6
	v_rcp_f32_e32 v6, v5
	v_add_f32_e32 v5, 1.0, v7
	v_mul_f32_e32 v7, 0x3e38aa3b, v24
	v_exp_f32_e32 v7, v7
	v_exp_f32_e32 v8, v8
	v_rcp_f32_e32 v24, v5
	v_mul_f32_e32 v9, 0x3e38aa3b, v9
	v_add_f32_e32 v5, 1.0, v7
	v_add_f32_e32 v7, 1.0, v8
	v_mul_f32_e32 v8, 0x3e38aa3b, v25
	v_exp_f32_e32 v8, v8
	v_exp_f32_e32 v9, v9
	v_rcp_f32_e32 v23, v7
	v_mul_f32_e32 v10, 0x3e38aa3b, v10
	v_add_f32_e32 v7, 1.0, v8
	v_add_f32_e32 v8, 1.0, v9
	v_mul_f32_e32 v9, 0x3e38aa3b, v26
	v_exp_f32_e32 v9, v9
	v_exp_f32_e32 v10, v10
	v_rcp_f32_e32 v25, v8
	v_mul_f32_e32 v11, 0x3e38aa3b, v11
	v_add_f32_e32 v8, 1.0, v9
	v_add_f32_e32 v9, 1.0, v10
	v_mul_f32_e32 v10, 0x3e38aa3b, v27
	v_exp_f32_e32 v10, v10
	v_exp_f32_e32 v11, v11
	v_rcp_f32_e32 v26, v9
	v_mul_f32_e32 v12, 0x3e38aa3b, v12
	v_add_f32_e32 v9, 1.0, v10
	v_rcp_f32_e32 v10, v9
	v_add_f32_e32 v9, 1.0, v11
	v_mul_f32_e32 v11, 0x3e38aa3b, v28
	v_exp_f32_e32 v11, v11
	v_exp_f32_e32 v27, v12
	v_rcp_f32_e32 v12, v9
	v_mul_f32_e32 v14, 0x3e38aa3b, v14
	v_add_f32_e32 v9, 1.0, v11
	v_add_f32_e32 v11, 1.0, v27
	v_mul_f32_e32 v27, 0x3e38aa3b, v29
	v_exp_f32_e32 v28, v27
	v_rcp_f32_e32 v27, v11
	v_exp_f32_e32 v29, v14
	v_mul_f32_e32 v15, 0x3e38aa3b, v15
	v_add_f32_e32 v11, 1.0, v28
	v_mul_f32_e32 v28, 0x3e38aa3b, v30
	v_exp_f32_e32 v28, v28
	v_mul_f32_e32 v13, 0x3e38aa3b, v13
	v_exp_f32_e32 v15, v15
	v_mul_f32_e32 v16, 0x3e38aa3b, v16
	v_add_f32_e32 v14, 1.0, v28
	v_add_f32_e32 v28, 1.0, v29
	v_mul_f32_e32 v29, 0x3e38aa3b, v31
	v_exp_f32_e32 v29, v29
	v_mul_f32_e32 v17, 0x3e38aa3b, v17
	v_exp_f32_e32 v13, v13
	v_exp_f32_e32 v31, v16
	v_add_f32_e32 v29, 1.0, v29
	v_rcp_f32_e32 v30, v29
	v_mul_f32_e32 v29, 0x3e38aa3b, v32
	v_exp_f32_e32 v29, v29
	v_exp_f32_e32 v17, v17
	v_add_f32_e32 v15, 1.0, v15
	v_add_f32_e32 v13, 1.0, v13
	v_rcp_f32_e32 v16, v15
	v_add_f32_e32 v15, 1.0, v29
	v_add_f32_e32 v29, 1.0, v31
	v_add_f32_e32 v17, 1.0, v17
	v_rcp_f32_e32 v13, v13
	v_rcp_f32_e32 v28, v28
	v_rcp_f32_e32 v29, v29
	v_rcp_f32_e32 v17, v17
	v_mul_f32 v80, v26, v12
	v_mul_f32 v81, v27, v13
	v_rcp_f32_e32 v66, v66
	v_mul_f32 v80, v80, v81
	v_mov_b32_e32 v81, v80
	v_mul_f32 v90, v28, v16
	v_mul_f32 v91, v29, v17
	v_mul_f32_e32 v31, 0x3e38aa3b, v33
	v_mul_f32 v90, v90, v91
	v_mov_b32_e32 v91, v90
	v_exp_f32_e32 v31, v31
	v_mov_b32_e32 v81, v90
	s_nop 1
	v_permlane32_swap_b32_e32 v90, v81
	v_mov_b32_e32 v86, v80
	v_fma_f32 v91, v81, v134, v135
	s_nop 0
	v_permlane32_swap_b32_e32 v80, v86
	v_mov_b32_e32 v87, v90
	v_mul_f32_e32 v90, v17, v91
	v_mul_f32 v68, v66, v20
	v_mul_f32 v69, v67, v21
	v_mul_f32 v76, v22, v24
	v_mul_f32 v77, v23, v25
	v_mov_b32_e32 v92, v29
	v_mov_b32_e32 v93, v17
	v_mov_b32_e32 v94, v28
	v_mul_f32_e32 v17, v29, v90
	v_mul_f32 v28, v80, v86
	v_mul_f32 v29, v81, v87
	v_mul_f32 v68, v68, v69
	v_mov_b32_e32 v69, v68
	v_mul_f32 v76, v76, v77
	v_mov_b32_e32 v77, v76
	v_mul_f32 v80, v28, v29
	v_mul_f32 v81, v29, v28
	v_fma_f32 v28, v86, v134, v135
	v_add_f32_e32 v31, 1.0, v31
	v_mov_b32_e32 v69, v76
	v_mov_b32_e32 v86, v27
	v_mov_b32_e32 v87, v13
	v_mul_f32_e32 v29, v28, v29
	v_rcp_f32_e32 v14, v14
	v_rcp_f32_e32 v15, v15
	v_rcp_f32_e32 v31, v31
	v_permlane32_swap_b32_e32 v76, v69
	v_sub_f32 v86, 1.0, v86
	v_sub_f32 v87, 1.0, v87
	v_mul_f32_e32 v28, v13, v29
	v_mul_f32 v86, v86, v28
	v_mul_f32 v87, v87, v29
	v_mul_f32_e32 v13, v27, v28
	v_fma_f32 v28, v69, v134, v135
	v_exp_f32_e32 v18, v18
	v_mul_f32_e32 v29, v28, v80
	v_rcp_f32_e32 v8, v8
	v_rcp_f32_e32 v9, v9
	v_rcp_f32_e32 v11, v11
	v_mov_b32_e32 v72, v68
	v_sub_f32 v92, 1.0, v92
	v_sub_f32 v93, 1.0, v93
	v_mul_f32_e32 v28, v25, v29
	v_permlane32_swap_b32_e32 v68, v72
	v_mul_f32 v88, v14, v30
	v_mul_f32 v89, v15, v31
	v_mul_f32 v92, v92, v90
	v_mul_f32 v93, v93, v91
	v_mov_b32_e32 v90, v26
	v_mul_f32_e32 v73, v69, v76
	v_mov_b32_e32 v26, v23
	v_mov_b32_e32 v27, v25
	v_mul_f32_e32 v23, v23, v28
	v_mov_b32_e32 v69, v80
	v_mul_f32 v88, v88, v89
	v_mov_b32_e32 v89, v88
	v_sub_f32 v26, 1.0, v26
	v_sub_f32 v27, 1.0, v27
	v_mov_b32_e32 v76, v22
	v_mov_b32_e32 v77, v24
	v_mul_f32_e32 v22, v24, v23
	v_mul_f32 v24, v72, v68
	v_mul_f32 v25, v73, v69
	v_add_f32_e32 v18, 1.0, v18
	v_mov_b32_e32 v71, v88
	v_mul_f32 v26, v26, v28
	v_mul_f32 v27, v27, v29
	v_mul_f32 v28, v24, v25
	v_mul_f32 v29, v25, v24
	v_fma_f32 v24, v72, v134, v135
	v_rcp_f32_e32 v18, v18
	v_rcp_f32_e32 v3, v3
	v_rcp_f32_e32 v4, v4
	v_rcp_f32_e32 v5, v5
	v_rcp_f32_e32 v7, v7
	v_mul_f32 v78, v8, v10
	v_mul_f32 v79, v9, v11
	v_permlane32_swap_b32_e32 v88, v71
	v_mul_f32_e32 v25, v24, v25
	v_mul_f32 v78, v78, v79
	v_mov_b32_e32 v79, v78
	v_mov_b32_e32 v68, v67
	v_mov_b32_e32 v69, v21
	v_mul_f32_e32 v24, v21, v25
	v_fma_f32 v29, v71, v134, v135
	v_mov_b32_e32 v84, v78
	v_sub_f32 v76, 1.0, v76
	v_sub_f32 v77, 1.0, v77
	v_sub_f32 v68, 1.0, v68
	v_sub_f32 v69, 1.0, v69
	v_mul_f32_e32 v21, v67, v24
	v_mul_f32_e32 v67, v29, v28
	v_permlane32_swap_b32_e32 v78, v84
	v_mul_f32 v22, v76, v22
	v_mul_f32 v23, v77, v23
	v_mul_f32 v76, v68, v24
	v_mul_f32 v77, v69, v25
	v_mov_b32_e32 v68, v66
	v_mov_b32_e32 v69, v20
	v_mul_f32_e32 v85, v71, v88
	v_mul_f32_e32 v66, v31, v67
	v_mov_b32_e32 v79, v28
	v_mul_f32 v32, v2, v18
	v_mul_f32 v33, v3, v19
	v_mul_f32 v74, v4, v6
	v_mul_f32 v75, v5, v7
	v_sub_f32 v68, 1.0, v68
	v_sub_f32 v69, 1.0, v69
	v_mul_f32_e32 v20, v20, v21
	v_mov_b32_e32 v24, v15
	v_mov_b32_e32 v25, v31
	v_mul_f32_e32 v15, v15, v66
	v_mul_f32 v28, v84, v78
	v_mul_f32 v29, v85, v79
	v_mul_f32 v32, v32, v33
	v_mov_b32_e32 v33, v32
	v_mul_f32 v74, v74, v75
	v_mov_b32_e32 v75, v74
	v_mul_f32 v20, v68, v20
	v_mul_f32 v21, v69, v21
	v_sub_f32 v24, 1.0, v24
	v_sub_f32 v25, 1.0, v25
	v_mov_b32_e32 v68, v14
	v_mov_b32_e32 v69, v30
	v_mul_f32_e32 v14, v30, v15
	v_mul_f32 v30, v28, v29
	v_mul_f32 v31, v29, v28
	v_fma_f32 v28, v84, v134, v135
	v_mov_b32_e32 v33, v74
	v_mul_f32 v24, v24, v66
	v_mul_f32 v25, v25, v67
	v_mov_b32_e32 v66, v9
	v_mov_b32_e32 v67, v11
	v_mul_f32_e32 v29, v28, v29
	v_permlane32_swap_b32_e32 v74, v33
	v_sub_f32 v66, 1.0, v66
	v_sub_f32 v67, 1.0, v67
	v_mul_f32_e32 v28, v11, v29
	v_mul_f32 v72, v66, v28
	v_mul_f32 v73, v67, v29
	v_mul_f32_e32 v9, v9, v28
	v_fma_f32 v28, v33, v134, v135
	v_mul_f32_e32 v29, v28, v30
	v_mov_b32_e32 v70, v32
	v_mov_b32_e32 v66, v8
	v_mov_b32_e32 v67, v10
	v_mul_f32_e32 v28, v7, v29
	v_permlane32_swap_b32_e32 v32, v70
	v_sub_f32 v66, 1.0, v66
	v_sub_f32 v67, 1.0, v67
	v_mul_f32_e32 v8, v10, v9
	v_mul_f32_e32 v71, v33, v74
	v_mov_b32_e32 v10, v5
	v_mul_f32_e32 v5, v5, v28
	v_mov_b32_e32 v33, v30
	v_mul_f32 v8, v66, v8
	v_mul_f32 v9, v67, v9
	v_mov_b32_e32 v11, v7
	v_mov_b32_e32 v66, v4
	v_mov_b32_e32 v67, v6
	v_mul_f32_e32 v4, v6, v5
	v_mul_f32 v6, v70, v32
	v_mul_f32 v7, v71, v33
	v_sub_f32 v10, 1.0, v10
	v_sub_f32 v11, 1.0, v11
	v_mul_f32_e32 v123, v6, v7
	v_fma_f32 v6, v70, v134, v135
	v_mul_f32_e32 v7, v6, v7
	v_mul_f32_e32 v6, v19, v7
	v_mov_b32_e32 v95, v16
	v_mov_b32_e32 v91, v12
	v_mul_f32 v10, v10, v28
	v_mul_f32 v11, v11, v29
	v_mov_b32_e32 v28, v3
	v_mov_b32_e32 v29, v19
	v_mov_b32_e32 v30, v2
	v_mov_b32_e32 v31, v18
	v_mul_f32_e32 v3, v3, v6
	s_mov_b32 s4, 0x1f800000
	v_sub_f32 v94, 1.0, v94
	v_sub_f32 v95, 1.0, v95
	v_mul_f32_e32 v16, v16, v17
	v_sub_f32 v90, 1.0, v90
	v_sub_f32 v91, 1.0, v91
	v_mul_f32_e32 v12, v12, v13
	v_sub_f32 v68, 1.0, v68
	v_sub_f32 v69, 1.0, v69
	v_sub_f32 v66, 1.0, v66
	v_sub_f32 v67, 1.0, v67
	v_sub_f32 v28, 1.0, v28
	v_sub_f32 v29, 1.0, v29
	v_sub_f32 v30, 1.0, v30
	v_sub_f32 v31, 1.0, v31
	v_mul_f32_e32 v2, v18, v3
	v_cmp_gt_f32_e32 vcc, s4, v123
	v_readlane_b32 s6, v255, 3
	v_mul_f32 v16, v94, v16
	v_mul_f32 v17, v95, v17
	v_mul_f32 v12, v90, v12
	v_mul_f32 v13, v91, v13
	v_mul_f32 v14, v68, v14
	v_mul_f32 v15, v69, v15
	v_mul_f32 v4, v66, v4
	v_mul_f32 v5, v67, v5
	v_mul_f32 v28, v28, v6
	v_mul_f32 v29, v29, v7
	v_mul_f32 v2, v30, v2
	v_mul_f32 v3, v31, v3
	s_cmp_eq_u64 vcc, exec
	v_readlane_b32 s7, v255, 4
	s_mov_b32 s94, s67
	s_cselect_b64 s[4:5], -1, 0
	v_cvt_pk_bf16_f32 v66, v2, v3
	v_cvt_pk_bf16_f32 v67, v28, v29
	v_cvt_pk_bf16_f32 v68, v4, v5
	v_cvt_pk_bf16_f32 v69, v10, v11
	v_cvt_pk_bf16_f32 v70, v8, v9
	v_cvt_pk_bf16_f32 v71, v72, v73
	v_cvt_pk_bf16_f32 v72, v14, v15
	v_cvt_pk_bf16_f32 v73, v24, v25
	v_cvt_pk_bf16_f32 v74, v20, v21
	v_cvt_pk_bf16_f32 v75, v76, v77
	v_cvt_pk_bf16_f32 v76, v22, v23
	v_cvt_pk_bf16_f32 v77, v26, v27
	v_cvt_pk_bf16_f32 v78, v12, v13
	v_cvt_pk_bf16_f32 v79, v86, v87
	v_cvt_pk_bf16_f32 v80, v16, v17
	s_andn2_b64 vcc, exec, s[6:7]
	v_cvt_pk_bf16_f32 v81, v92, v93
	s_cbranch_vccnz .LBB0_350
	v_mfma_f32_32x32x16_bf16 v[18:33], v[34:37], v[66:69], 0
	s_mov_b64 s[72:73], 0
	s_waitcnt lgkmcnt(10)
	v_mfma_f32_32x32x16_bf16 v[2:17], v[38:41], v[66:69], 0
	v_mfma_f32_32x32x16_bf16 v[18:33], v[42:45], v[70:73], v[18:33]
	s_waitcnt lgkmcnt(8)
	v_mfma_f32_32x32x16_bf16 v[2:17], v[46:49], v[70:73], v[2:17]
	s_waitcnt lgkmcnt(6)
	v_mfma_f32_32x32x16_bf16 v[18:33], v[50:53], v[74:77], v[18:33]
	s_waitcnt lgkmcnt(2)
	v_mfma_f32_32x32x16_bf16 v[2:17], v[54:57], v[74:77], v[2:17]
	v_mfma_f32_32x32x16_bf16 v[18:33], v[58:61], v[78:81], v[18:33]
	s_waitcnt lgkmcnt(0)
	v_mfma_f32_32x32x16_bf16 v[2:17], v[62:65], v[78:81], v[2:17]
	s_branch .LBB0_351

.LBB0_370:
	v_mul_f32_e32 v82, 0x3e38aa3b, v82
	v_exp_f32_e32 v82, v82
	s_nop 7
	v_mul_f32_e32 v66, 0x3e38aa3b, v66
	v_exp_f32_e32 v66, v66
	v_mul_f32_e32 v67, 0x3e38aa3b, v67
	v_add_f32_e32 v82, 1.0, v82
	v_exp_f32_e32 v67, v67
	v_add_f32_e32 v122, 1.0, v66
	v_rcp_f32_e32 v66, v82
	v_mul_f32_e32 v82, 0x3e38aa3b, v83
	v_mul_f32_e32 v83, 0x3e38aa3b, v84
	v_exp_f32_e32 v83, v83
	v_add_f32_e32 v67, 1.0, v67
	v_mul_f32_e32 v68, 0x3e38aa3b, v68
	v_exp_f32_e32 v68, v68
	v_rcp_f32_e32 v84, v67
	v_add_f32_e32 v67, 1.0, v83
	v_mul_f32_e32 v83, 0x3e38aa3b, v85
	v_exp_f32_e32 v83, v83
	v_mul_f32_e32 v69, 0x3e38aa3b, v69
	v_exp_f32_e32 v69, v69
	v_add_f32_e32 v68, 1.0, v68
	v_rcp_f32_e32 v125, v68
	v_add_f32_e32 v68, 1.0, v83
	v_rcp_f32_e32 v83, v68
	v_add_f32_e32 v68, 1.0, v69
	v_mul_f32_e32 v69, 0x3e38aa3b, v86
	v_mul_f32_e32 v70, 0x3e38aa3b, v70
	v_exp_f32_e32 v69, v69
	v_exp_f32_e32 v70, v70
	v_rcp_f32_e32 v85, v68
	v_mul_f32_e32 v71, 0x3e38aa3b, v71
	v_add_f32_e32 v68, 1.0, v69
	v_add_f32_e32 v69, 1.0, v70
	v_mul_f32_e32 v70, 0x3e38aa3b, v87
	v_exp_f32_e32 v70, v70
	v_exp_f32_e32 v71, v71
	v_rcp_f32_e32 v86, v69
	v_mul_f32_e32 v72, 0x3e38aa3b, v72
	v_add_f32_e32 v69, 1.0, v70
	v_rcp_f32_e32 v70, v69
	v_add_f32_e32 v69, 1.0, v71
	v_mul_f32_e32 v71, 0x3e38aa3b, v88
	v_exp_f32_e32 v71, v71
	v_exp_f32_e32 v72, v72
	v_rcp_f32_e32 v88, v69
	v_mul_f32_e32 v73, 0x3e38aa3b, v73
	v_add_f32_e32 v69, 1.0, v71
	v_add_f32_e32 v71, 1.0, v72
	v_mul_f32_e32 v72, 0x3e38aa3b, v89
	v_exp_f32_e32 v72, v72
	v_exp_f32_e32 v73, v73
	v_rcp_f32_e32 v87, v71
	v_mul_f32_e32 v74, 0x3e38aa3b, v74
	v_add_f32_e32 v71, 1.0, v72
	v_add_f32_e32 v72, 1.0, v73
	v_mul_f32_e32 v73, 0x3e38aa3b, v90
	v_exp_f32_e32 v73, v73
	v_exp_f32_e32 v74, v74
	v_rcp_f32_e32 v89, v72
	v_mul_f32_e32 v75, 0x3e38aa3b, v75
	v_add_f32_e32 v72, 1.0, v73
	v_add_f32_e32 v73, 1.0, v74
	v_mul_f32_e32 v74, 0x3e38aa3b, v91
	v_exp_f32_e32 v74, v74
	v_exp_f32_e32 v75, v75
	v_rcp_f32_e32 v90, v73
	v_mul_f32_e32 v76, 0x3e38aa3b, v76
	v_add_f32_e32 v73, 1.0, v74
	v_rcp_f32_e32 v74, v73
	v_add_f32_e32 v73, 1.0, v75
	v_mul_f32_e32 v75, 0x3e38aa3b, v92
	v_exp_f32_e32 v75, v75
	v_exp_f32_e32 v91, v76
	v_rcp_f32_e32 v76, v73
	v_mul_f32_e32 v78, 0x3e38aa3b, v78
	v_add_f32_e32 v73, 1.0, v75
	v_add_f32_e32 v75, 1.0, v91
	v_mul_f32_e32 v91, 0x3e38aa3b, v93
	v_exp_f32_e32 v92, v91
	v_rcp_f32_e32 v91, v75
	v_exp_f32_e32 v93, v78
	v_mul_f32_e32 v79, 0x3e38aa3b, v79
	v_add_f32_e32 v75, 1.0, v92
	v_mul_f32_e32 v92, 0x3e38aa3b, v94
	v_exp_f32_e32 v92, v92
	v_exp_f32_e32 v79, v79
	v_mul_f32_e32 v80, 0x3e38aa3b, v80
	v_mul_f32_e32 v81, 0x3e38aa3b, v81
	v_add_f32_e32 v78, 1.0, v92
	v_add_f32_e32 v92, 1.0, v93
	v_mul_f32_e32 v93, 0x3e38aa3b, v95
	v_exp_f32_e32 v93, v93
	v_exp_f32_e32 v95, v80
	v_exp_f32_e32 v81, v81
	v_mul_f32_e32 v77, 0x3e38aa3b, v77
	v_add_f32_e32 v93, 1.0, v93
	v_rcp_f32_e32 v94, v93
	v_mul_f32_e32 v93, 0x3e38aa3b, v96
	v_exp_f32_e32 v93, v93
	v_exp_f32_e32 v77, v77
	v_add_f32_e32 v79, 1.0, v79
	v_rcp_f32_e32 v80, v79
	v_add_f32_e32 v79, 1.0, v93
	v_add_f32_e32 v93, 1.0, v95
	v_add_f32_e32 v81, 1.0, v81
	v_rcp_f32_e32 v92, v92
	v_rcp_f32_e32 v93, v93
	v_rcp_f32_e32 v81, v81
	v_add_f32_e32 v77, 1.0, v77
	v_rcp_f32_e32 v77, v77
	v_rcp_f32_e32 v124, v122
	v_mul_f32 v180, v92, v80
	v_mul_f32 v181, v93, v81
	v_mov_b32_e32 v182, v93
	v_mul_f32 v180, v180, v181
	v_mov_b32_e32 v181, v180
	v_mul_f32 v148, v90, v76
	v_mul_f32 v149, v91, v77
	v_mov_b32_e32 v141, v180
	v_mul_f32 v148, v148, v149
	v_mov_b32_e32 v149, v148
	s_nop 0
	v_permlane32_swap_b32_e32 v180, v141
	v_mul_f32_e32 v149, v141, v180
	v_fma_f32 v141, v141, v134, v135
	v_mov_b32_e32 v122, v148
	v_mul_f32_e32 v181, v123, v141
	s_nop 0
	v_permlane32_swap_b32_e32 v148, v122
	v_mul_f32_e32 v180, v81, v181
	v_mov_b32_e32 v183, v81
	v_mov_b32_e32 v184, v92
	v_mul_f32_e32 v81, v93, v180
	v_mul_f32 v92, v122, v148
	v_mul_f32 v93, v123, v149
	v_mul_f32_e32 v95, 0x3e38aa3b, v97
	v_mul_f32 v136, v124, v84
	v_mul_f32 v137, v125, v85
	v_mul_f32 v144, v86, v88
	v_mul_f32 v145, v87, v89
	v_mul_f32 v148, v92, v93
	v_mul_f32 v149, v93, v92
	v_fma_f32 v92, v122, v134, v135
	v_exp_f32_e32 v95, v95
	v_mul_f32 v136, v136, v137
	v_mov_b32_e32 v137, v136
	v_mul_f32 v144, v144, v145
	v_mov_b32_e32 v145, v144
	v_mov_b32_e32 v122, v91
	v_mov_b32_e32 v123, v77
	v_mul_f32_e32 v93, v92, v93
	v_mov_b32_e32 v137, v144
	v_sub_f32 v182, 1.0, v182
	v_sub_f32 v183, 1.0, v183
	v_sub_f32 v122, 1.0, v122
	v_sub_f32 v123, 1.0, v123
	v_mul_f32_e32 v92, v77, v93
	v_permlane32_swap_b32_e32 v144, v137
	v_mul_f32 v182, v182, v180
	v_mul_f32 v183, v183, v181
	v_mul_f32 v180, v122, v92
	v_mul_f32 v181, v123, v93
	v_mov_b32_e32 v122, v90
	v_mov_b32_e32 v123, v76
	v_mul_f32_e32 v77, v91, v92
	v_sub_f32 v122, 1.0, v122
	v_sub_f32 v123, 1.0, v123
	v_mul_f32_e32 v76, v76, v77
	v_fma_f32 v92, v137, v134, v135
	v_add_f32_e32 v95, 1.0, v95
	v_mul_f32 v90, v122, v76
	v_mul_f32 v91, v123, v77
	v_mov_b32_e32 v76, v87
	v_mov_b32_e32 v77, v89
	v_mul_f32_e32 v93, v92, v148
	v_rcp_f32_e32 v78, v78
	v_rcp_f32_e32 v79, v79
	v_rcp_f32_e32 v95, v95
	v_sub_f32 v76, 1.0, v76
	v_sub_f32 v77, 1.0, v77
	v_mul_f32_e32 v92, v89, v93
	v_mov_b32_e32 v140, v136
	v_mul_f32_e32 v141, v137, v144
	v_mul_f32 v144, v76, v92
	v_mul_f32 v145, v77, v93
	v_mov_b32_e32 v76, v86
	v_mov_b32_e32 v77, v88
	v_mul_f32_e32 v87, v87, v92
	v_exp_f32_e32 v82, v82
	v_permlane32_swap_b32_e32 v136, v140
	v_sub_f32 v76, 1.0, v76
	v_sub_f32 v77, 1.0, v77
	v_mul_f32_e32 v86, v88, v87
	v_mov_b32_e32 v137, v148
	v_rcp_f32_e32 v72, v72
	v_rcp_f32_e32 v73, v73
	v_rcp_f32_e32 v75, v75
	v_mul_f32 v76, v76, v86
	v_mul_f32 v77, v77, v87
	v_mul_f32 v86, v140, v136
	v_mul_f32 v87, v141, v137
	v_mul_f32 v178, v78, v94
	v_mul_f32 v179, v79, v95
	v_mul_f32 v88, v86, v87
	v_mul_f32 v89, v87, v86
	v_fma_f32 v86, v140, v134, v135
	v_mul_f32 v178, v178, v179
	v_mov_b32_e32 v179, v178
	v_mul_f32_e32 v87, v86, v87
	v_add_f32_e32 v82, 1.0, v82
	v_mov_b32_e32 v139, v178
	v_mul_f32_e32 v86, v85, v87
	v_rcp_f32_e32 v82, v82
	v_rcp_f32_e32 v67, v67
	v_rcp_f32_e32 v68, v68
	v_rcp_f32_e32 v69, v69
	v_rcp_f32_e32 v71, v71
	v_mul_f32 v146, v72, v74
	v_mul_f32 v147, v73, v75
	v_permlane32_swap_b32_e32 v178, v139
	v_mov_b32_e32 v93, v85
	v_mov_b32_e32 v122, v124
	v_mov_b32_e32 v123, v84
	v_mul_f32_e32 v85, v125, v86
	v_mul_f32 v146, v146, v147
	v_mov_b32_e32 v147, v146
	v_sub_f32 v122, 1.0, v122
	v_sub_f32 v123, 1.0, v123
	v_mul_f32_e32 v84, v84, v85
	v_fma_f32 v89, v139, v134, v135
	v_mov_b32_e32 v150, v146
	v_mov_b32_e32 v92, v125
	v_mul_f32 v84, v122, v84
	v_mul_f32 v85, v123, v85
	v_mul_f32_e32 v123, v89, v88
	v_permlane32_swap_b32_e32 v146, v150
	v_sub_f32 v92, 1.0, v92
	v_sub_f32 v93, 1.0, v93
	v_mul_f32_e32 v151, v139, v178
	v_mul_f32_e32 v122, v95, v123
	v_mov_b32_e32 v147, v88
	v_mul_f32 v96, v66, v82
	v_mul_f32 v97, v67, v83
	v_mul_f32 v142, v68, v70
	v_mul_f32 v143, v69, v71
	v_mul_f32 v92, v92, v86
	v_mul_f32 v93, v93, v87
	v_mov_b32_e32 v86, v79
	v_mov_b32_e32 v87, v95
	v_mul_f32_e32 v79, v79, v122
	v_mul_f32 v88, v150, v146
	v_mul_f32 v89, v151, v147
	v_mul_f32 v96, v96, v97
	v_mov_b32_e32 v97, v96
	v_mul_f32 v142, v142, v143
	v_mov_b32_e32 v143, v142
	v_sub_f32 v86, 1.0, v86
	v_sub_f32 v87, 1.0, v87
	v_mov_b32_e32 v124, v78
	v_mov_b32_e32 v125, v94
	v_mul_f32_e32 v78, v94, v79
	v_mul_f32 v94, v88, v89
	v_mul_f32 v95, v89, v88
	v_fma_f32 v88, v150, v134, v135
	v_mov_b32_e32 v97, v142
	v_mul_f32 v86, v86, v122
	v_mul_f32 v87, v87, v123
	v_mov_b32_e32 v122, v73
	v_mov_b32_e32 v123, v75
	v_mul_f32_e32 v89, v88, v89
	v_permlane32_swap_b32_e32 v142, v97
	v_sub_f32 v124, 1.0, v124
	v_sub_f32 v125, 1.0, v125
	v_sub_f32 v122, 1.0, v122
	v_sub_f32 v123, 1.0, v123
	v_mul_f32_e32 v88, v75, v89
	v_mul_f32 v78, v124, v78
	v_mul_f32 v79, v125, v79
	v_mul_f32 v124, v122, v88
	v_mul_f32 v125, v123, v89
	v_mul_f32_e32 v73, v73, v88
	v_fma_f32 v88, v97, v134, v135
	v_mov_b32_e32 v122, v72
	v_mov_b32_e32 v123, v74
	v_mul_f32_e32 v89, v88, v94
	v_mov_b32_e32 v138, v96
	v_sub_f32 v122, 1.0, v122
	v_sub_f32 v123, 1.0, v123
	v_mul_f32_e32 v72, v74, v73
	v_mul_f32_e32 v88, v71, v89
	v_permlane32_swap_b32_e32 v96, v138
	v_mul_f32 v72, v122, v72
	v_mul_f32 v73, v123, v73
	v_mul_f32_e32 v139, v97, v142
	v_mov_b32_e32 v74, v69
	v_mov_b32_e32 v122, v68
	v_mov_b32_e32 v123, v70
	v_mul_f32_e32 v69, v69, v88
	v_mov_b32_e32 v97, v94
	v_mov_b32_e32 v75, v71
	v_sub_f32 v122, 1.0, v122
	v_sub_f32 v123, 1.0, v123
	v_mul_f32_e32 v68, v70, v69
	v_mul_f32 v70, v138, v96
	v_mul_f32 v71, v139, v97
	v_mul_f32 v68, v122, v68
	v_mul_f32 v69, v123, v69
	v_mul_f32_e32 v123, v70, v71
	v_fma_f32 v70, v138, v134, v135
	v_mul_f32_e32 v71, v70, v71
	v_sub_f32 v74, 1.0, v74
	v_sub_f32 v75, 1.0, v75
	v_mul_f32_e32 v70, v83, v71
	v_mov_b32_e32 v185, v80
	v_mul_f32 v74, v74, v88
	v_mul_f32 v75, v75, v89
	v_mov_b32_e32 v88, v67
	v_mov_b32_e32 v89, v83
	v_mov_b32_e32 v94, v66
	v_mov_b32_e32 v95, v82
	v_mul_f32_e32 v67, v67, v70
	s_mov_b32 s72, 0x1f800000
	v_sub_f32 v184, 1.0, v184
	v_sub_f32 v185, 1.0, v185
	v_mul_f32_e32 v80, v80, v81
	v_sub_f32 v88, 1.0, v88
	v_sub_f32 v89, 1.0, v89
	v_sub_f32 v94, 1.0, v94
	v_sub_f32 v95, 1.0, v95
	v_mul_f32_e32 v66, v82, v67
	v_cmp_gt_f32_e32 vcc, s72, v123
	v_readlane_b32 s72, v255, 3
	v_mul_f32 v80, v184, v80
	v_mul_f32 v81, v185, v81
	v_mul_f32 v88, v88, v70
	v_mul_f32 v89, v89, v71
	v_mul_f32 v66, v94, v66
	v_mul_f32 v67, v95, v67
	s_cmp_eq_u64 vcc, exec
	v_readlane_b32 s73, v255, 4
	s_cselect_b64 s[84:85], -1, 0
	v_cvt_pk_bf16_f32 v66, v66, v67
	v_cvt_pk_bf16_f32 v67, v88, v89
	v_cvt_pk_bf16_f32 v68, v68, v69
	v_cvt_pk_bf16_f32 v69, v74, v75
	v_cvt_pk_bf16_f32 v70, v72, v73
	v_cvt_pk_bf16_f32 v71, v124, v125
	v_cvt_pk_bf16_f32 v72, v78, v79
	v_cvt_pk_bf16_f32 v73, v86, v87
	v_cvt_pk_bf16_f32 v74, v84, v85
	v_cvt_pk_bf16_f32 v75, v92, v93
	v_cvt_pk_bf16_f32 v76, v76, v77
	v_cvt_pk_bf16_f32 v77, v144, v145
	v_cvt_pk_bf16_f32 v78, v90, v91
	v_cvt_pk_bf16_f32 v79, v180, v181
	v_cvt_pk_bf16_f32 v80, v80, v81
	v_cvt_pk_bf16_f32 v81, v182, v183
	s_andn2_b64 vcc, exec, s[72:73]
	s_mov_b64 s[72:73], -1
	s_cbranch_vccnz .LBB0_372
	v_mfma_f32_32x32x16_bf16 v[18:33], v[34:37], v[66:69], v[18:33]
	s_mov_b64 s[72:73], 0
	s_waitcnt lgkmcnt(10)
	v_mfma_f32_32x32x16_bf16 v[2:17], v[38:41], v[66:69], v[2:17]
	v_mfma_f32_32x32x16_bf16 v[18:33], v[42:45], v[70:73], v[18:33]
	s_waitcnt lgkmcnt(8)
	v_mfma_f32_32x32x16_bf16 v[2:17], v[46:49], v[70:73], v[2:17]
	s_waitcnt lgkmcnt(6)
	v_mfma_f32_32x32x16_bf16 v[18:33], v[50:53], v[74:77], v[18:33]
	s_waitcnt lgkmcnt(2)
	v_mfma_f32_32x32x16_bf16 v[2:17], v[54:57], v[74:77], v[2:17]
	v_mfma_f32_32x32x16_bf16 v[18:33], v[58:61], v[78:81], v[18:33]
	s_waitcnt lgkmcnt(0)
	v_mfma_f32_32x32x16_bf16 v[2:17], v[62:65], v[78:81], v[2:17]

.LBB0_384:
	s_or_b64 exec, exec, s[4:5]
	v_lshl_add_u64 v[34:35], v[120:121], 1, s[2:3]
	s_waitcnt lgkmcnt(9)
	v_lshlrev_b64 v[46:47], 1, v[114:115]
	v_lshl_add_u64 v[34:35], v[34:35], 0, v[46:47]
	s_mov_b64 s[2:3], 0x3000000
	v_lshl_add_u64 v[36:37], v[34:35], 0, s[2:3]
	v_add_co_u32_e32 v34, vcc, 0x3000000, v34
	v_readlane_b32 s2, v255, 49
	s_nop 0
	v_addc_co_u32_e32 v35, vcc, 0, v35, vcc
	s_waitcnt lgkmcnt(7)
	global_load_dwordx4 v[48:51], v[34:35], off
	global_load_dwordx4 v[42:45], v[36:37], off offset:64
	global_load_dwordx4 v[38:41], v[36:37], off offset:32
	s_nop 0
	global_load_dwordx4 v[34:37], v[36:37], off offset:96
	v_lshl_add_u32 v0, s2, 11, v0
	s_waitcnt lgkmcnt(6)
	v_lshlrev_b64 v[52:53], 11, v[0:1]
	v_readlane_b32 s2, v255, 50
	v_lshl_add_u64 v[52:53], s[56:57], 0, v[52:53]
	s_lshl_b32 s80, s2, 7
	v_lshl_add_u64 v[52:53], v[52:53], 0, s[80:81]
	v_lshl_add_u64 v[46:47], v[52:53], 0, v[46:47]
	s_waitcnt vmcnt(0) lgkmcnt(0)
	s_barrier
	s_mov_b64 s[2:3], 0
	s_waitcnt vmcnt(3)
	v_mov_b32_e32 v0, v50
	s_nop 1
	v_permlane32_swap_b32_e32 v48, v0
	v_lshlrev_b32_e32 v50, 16, v48
	s_waitcnt lgkmcnt(3)
	v_mov_b32_e32 v54, v51
	v_and_b32_e32 v51, 0xffff0000, v48
	v_mul_f32_e32 v48, 0xbfb8aa3b, v50
	v_exp_f32_e32 v48, v48
	v_permlane32_swap_b32_e32 v49, v54
	v_add_f32_e32 v48, 1.0, v48
	v_rcp_f32_e32 v52, v48
	v_mul_f32_e32 v48, 0xbfb8aa3b, v51
	v_exp_f32_e32 v48, v48
	s_nop 0
	v_add_f32_e32 v48, 1.0, v48
	v_rcp_f32_e32 v53, v48
	v_lshlrev_b32_e32 v48, 16, v49
	v_and_b32_e32 v49, 0xffff0000, v49
	v_mul_f32 v50, v52, v50
	v_mul_f32 v51, v53, v51
	s_nop 0
	v_mul_f32 v18, v18, v50
	v_mul_f32 v19, v19, v51
	s_nop 0
	v_cvt_pk_bf16_f32 v18, v18, v19
	v_mul_f32_e32 v19, 0xbfb8aa3b, v48
	v_exp_f32_e32 v19, v19
	s_nop 0
	v_add_f32_e32 v19, 1.0, v19
	v_rcp_f32_e32 v50, v19
	v_mul_f32_e32 v19, 0xbfb8aa3b, v49
	v_exp_f32_e32 v19, v19
	s_nop 0
	v_add_f32_e32 v19, 1.0, v19
	v_rcp_f32_e32 v51, v19
	s_nop 0
	v_mul_f32 v48, v50, v48
	v_mul_f32 v49, v51, v49
	s_nop 0
	v_mul_f32 v20, v20, v48
	v_mul_f32 v21, v21, v49
	s_nop 0
	v_cvt_pk_bf16_f32 v19, v20, v21
	v_lshlrev_b32_e32 v20, 16, v0
	v_and_b32_e32 v21, 0xffff0000, v0
	v_mul_f32_e32 v0, 0xbfb8aa3b, v20
	v_exp_f32_e32 v0, v0
	s_nop 0
	v_add_f32_e32 v0, 1.0, v0
	v_rcp_f32_e32 v48, v0
	v_mul_f32_e32 v0, 0xbfb8aa3b, v21
	v_exp_f32_e32 v0, v0
	s_nop 0
	v_add_f32_e32 v0, 1.0, v0
	v_rcp_f32_e32 v49, v0
	s_nop 0
	v_mul_f32 v20, v48, v20
	v_mul_f32 v21, v49, v21
	s_nop 0
	v_mul_f32 v20, v22, v20
	v_mul_f32 v21, v23, v21
	v_lshlrev_b32_e32 v22, 16, v54
	v_mul_f32_e32 v0, 0xbfb8aa3b, v22
	v_exp_f32_e32 v0, v0
	v_and_b32_e32 v23, 0xffff0000, v54
	v_cvt_pk_bf16_f32 v20, v20, v21
	s_nop 1
	v_permlane32_swap_b32_e32 v18, v20
	v_add_f32_e32 v0, 1.0, v0
	v_rcp_f32_e32 v48, v0
	v_mul_f32_e32 v0, 0xbfb8aa3b, v23
	v_exp_f32_e32 v0, v0
	s_nop 0
	v_add_f32_e32 v0, 1.0, v0
	v_rcp_f32_e32 v49, v0
	s_waitcnt vmcnt(2)
	v_mov_b32_e32 v0, v44
	s_nop 1
	v_permlane32_swap_b32_e32 v42, v0
	v_mul_f32 v22, v48, v22
	v_mul_f32 v23, v49, v23
	s_nop 0
	v_mul_f32 v22, v24, v22
	v_mul_f32 v23, v25, v23
	s_nop 0
	v_cvt_pk_bf16_f32 v21, v22, v23
	s_nop 1
	v_permlane32_swap_b32_e32 v19, v21
	global_store_dwordx4 v[46:47], v[18:21], off
	v_mov_b32_e32 v22, v45
	s_nop 1
	v_permlane32_swap_b32_e32 v43, v22
	v_lshlrev_b32_e32 v18, 16, v42
	v_and_b32_e32 v19, 0xffff0000, v42
	v_mul_f32_e32 v20, 0xbfb8aa3b, v18
	v_mul_f32_e32 v21, 0xbfb8aa3b, v19
	v_exp_f32_e32 v20, v20
	v_exp_f32_e32 v21, v21
	v_add_f32_e32 v20, 1.0, v20
	v_add_f32_e32 v21, 1.0, v21
	v_rcp_f32_e32 v20, v20
	v_rcp_f32_e32 v21, v21
	s_nop 0
	v_mul_f32 v18, v20, v18
	v_mul_f32 v19, v21, v19
	s_nop 0
	v_mul_f32 v2, v2, v18
	v_mul_f32 v3, v3, v19
	v_lshlrev_b32_e32 v18, 16, v43
	v_cvt_pk_bf16_f32 v2, v2, v3
	v_mul_f32_e32 v3, 0xbfb8aa3b, v18
	v_exp_f32_e32 v3, v3
	v_and_b32_e32 v19, 0xffff0000, v43
	v_add_f32_e32 v3, 1.0, v3
	v_rcp_f32_e32 v20, v3
	v_mul_f32_e32 v3, 0xbfb8aa3b, v19
	v_exp_f32_e32 v3, v3
	s_nop 0
	v_add_f32_e32 v3, 1.0, v3
	v_rcp_f32_e32 v21, v3
	s_nop 0
	v_mul_f32 v18, v20, v18
	v_mul_f32 v19, v21, v19
	s_nop 0
	v_mul_f32 v4, v4, v18
	v_mul_f32 v5, v5, v19
	s_nop 0
	v_cvt_pk_bf16_f32 v3, v4, v5
	v_lshlrev_b32_e32 v4, 16, v0
	v_and_b32_e32 v5, 0xffff0000, v0
	v_mul_f32_e32 v0, 0xbfb8aa3b, v4
	v_exp_f32_e32 v0, v0
	s_nop 0
	v_add_f32_e32 v0, 1.0, v0
	v_rcp_f32_e32 v18, v0
	v_mul_f32_e32 v0, 0xbfb8aa3b, v5
	v_exp_f32_e32 v0, v0
	s_nop 0
	v_add_f32_e32 v0, 1.0, v0
	v_rcp_f32_e32 v19, v0
	s_nop 0
	v_mul_f32 v4, v18, v4
	v_mul_f32 v5, v19, v5
	s_nop 0
	v_mul_f32 v4, v6, v4
	v_mul_f32 v5, v7, v5
	v_lshlrev_b32_e32 v6, 16, v22
	v_mul_f32_e32 v0, 0xbfb8aa3b, v6
	v_exp_f32_e32 v0, v0
	v_and_b32_e32 v7, 0xffff0000, v22
	v_cvt_pk_bf16_f32 v4, v4, v5
	s_nop 1
	v_permlane32_swap_b32_e32 v2, v4
	v_add_f32_e32 v0, 1.0, v0
	v_rcp_f32_e32 v18, v0
	v_mul_f32_e32 v0, 0xbfb8aa3b, v7
	v_exp_f32_e32 v0, v0
	s_nop 0
	v_add_f32_e32 v0, 1.0, v0
	v_rcp_f32_e32 v19, v0
	s_waitcnt vmcnt(2)
	v_mov_b32_e32 v0, v40
	s_nop 1
	v_permlane32_swap_b32_e32 v38, v0
	v_mul_f32 v6, v18, v6
	v_mul_f32 v7, v19, v7
	s_nop 0
	v_mul_f32 v6, v8, v6
	v_mul_f32 v7, v9, v7
	v_mov_b32_e32 v8, v41
	v_cvt_pk_bf16_f32 v5, v6, v7
	s_nop 1
	v_permlane32_swap_b32_e32 v3, v5
	global_store_dwordx4 v[46:47], v[2:5], off offset:64
	v_permlane32_swap_b32_e32 v39, v8
	s_nop 0
	v_lshlrev_b32_e32 v2, 16, v38
	v_and_b32_e32 v3, 0xffff0000, v38
	v_mul_f32_e32 v4, 0xbfb8aa3b, v2
	v_mul_f32_e32 v5, 0xbfb8aa3b, v3
	v_exp_f32_e32 v4, v4
	v_exp_f32_e32 v5, v5
	v_add_f32_e32 v4, 1.0, v4
	v_add_f32_e32 v5, 1.0, v5
	v_rcp_f32_e32 v4, v4
	v_rcp_f32_e32 v5, v5
	s_nop 0
	v_mul_f32 v2, v4, v2
	v_mul_f32 v3, v5, v3
	s_nop 0
	v_mul_f32 v2, v26, v2
	v_mul_f32 v3, v27, v3
	v_lshlrev_b32_e32 v4, 16, v39
	v_cvt_pk_bf16_f32 v2, v2, v3
	v_mul_f32_e32 v3, 0xbfb8aa3b, v4
	v_exp_f32_e32 v3, v3
	v_and_b32_e32 v5, 0xffff0000, v39
	v_add_f32_e32 v3, 1.0, v3
	v_rcp_f32_e32 v6, v3
	v_mul_f32_e32 v3, 0xbfb8aa3b, v5
	v_exp_f32_e32 v3, v3
	s_nop 0
	v_add_f32_e32 v3, 1.0, v3
	v_rcp_f32_e32 v7, v3
	s_nop 0
	v_mul_f32 v4, v6, v4
	v_mul_f32 v5, v7, v5
	s_nop 0
	v_mul_f32 v4, v28, v4
	v_mul_f32 v5, v29, v5
	s_nop 0
	v_cvt_pk_bf16_f32 v3, v4, v5
	v_lshlrev_b32_e32 v4, 16, v0
	v_and_b32_e32 v5, 0xffff0000, v0
	v_mul_f32_e32 v0, 0xbfb8aa3b, v4
	v_exp_f32_e32 v0, v0
	s_nop 0
	v_add_f32_e32 v0, 1.0, v0
	v_rcp_f32_e32 v6, v0
	v_mul_f32_e32 v0, 0xbfb8aa3b, v5
	v_exp_f32_e32 v0, v0
	s_nop 0
	v_add_f32_e32 v0, 1.0, v0
	v_rcp_f32_e32 v7, v0
	s_nop 0
	v_mul_f32 v4, v6, v4
	v_mul_f32 v5, v7, v5
	v_lshlrev_b32_e32 v6, 16, v8
	v_mul_f32_e32 v0, 0xbfb8aa3b, v6
	v_exp_f32_e32 v0, v0
	v_and_b32_e32 v7, 0xffff0000, v8
	v_mul_f32 v4, v30, v4
	v_mul_f32 v5, v31, v5
	v_add_f32_e32 v0, 1.0, v0
	v_rcp_f32_e32 v8, v0
	v_mul_f32_e32 v0, 0xbfb8aa3b, v7
	v_exp_f32_e32 v0, v0
	v_cvt_pk_bf16_f32 v4, v4, v5
	s_nop 1
	v_permlane32_swap_b32_e32 v2, v4
	v_add_f32_e32 v0, 1.0, v0
	v_rcp_f32_e32 v9, v0
	s_waitcnt vmcnt(2)
	v_mov_b32_e32 v0, v36
	s_nop 1
	v_permlane32_swap_b32_e32 v34, v0
	v_mul_f32 v6, v8, v6
	v_mul_f32 v7, v9, v7
	v_mov_b32_e32 v8, v37
	v_mul_f32 v6, v32, v6
	v_mul_f32 v7, v33, v7
	s_nop 0
	v_permlane32_swap_b32_e32 v35, v8
	v_cvt_pk_bf16_f32 v5, v6, v7
	s_nop 1
	v_permlane32_swap_b32_e32 v3, v5
	global_store_dwordx4 v[46:47], v[2:5], off offset:32
	s_nop 1
	v_lshlrev_b32_e32 v2, 16, v34
	v_and_b32_e32 v3, 0xffff0000, v34
	v_mul_f32_e32 v4, 0xbfb8aa3b, v2
	v_mul_f32_e32 v5, 0xbfb8aa3b, v3
	v_exp_f32_e32 v4, v4
	v_exp_f32_e32 v5, v5
	v_add_f32_e32 v4, 1.0, v4
	v_add_f32_e32 v5, 1.0, v5
	v_rcp_f32_e32 v4, v4
	v_rcp_f32_e32 v5, v5
	s_nop 0
	v_mul_f32 v2, v4, v2
	v_mul_f32 v3, v5, v3
	s_nop 0
	v_mul_f32 v2, v10, v2
	v_mul_f32 v3, v11, v3
	v_lshlrev_b32_e32 v4, 16, v35
	v_cvt_pk_bf16_f32 v2, v2, v3
	v_mul_f32_e32 v3, 0xbfb8aa3b, v4
	v_exp_f32_e32 v3, v3
	v_and_b32_e32 v5, 0xffff0000, v35
	v_add_f32_e32 v3, 1.0, v3
	v_rcp_f32_e32 v6, v3
	v_mul_f32_e32 v3, 0xbfb8aa3b, v5
	v_exp_f32_e32 v3, v3
	s_nop 0
	v_add_f32_e32 v3, 1.0, v3
	v_rcp_f32_e32 v7, v3
	s_nop 0
	v_mul_f32 v4, v6, v4
	v_mul_f32 v5, v7, v5
	s_nop 0
	v_mul_f32 v4, v12, v4
	v_mul_f32 v5, v13, v5
	s_nop 0
	v_cvt_pk_bf16_f32 v3, v4, v5
	v_lshlrev_b32_e32 v4, 16, v0
	v_and_b32_e32 v5, 0xffff0000, v0
	v_mul_f32_e32 v0, 0xbfb8aa3b, v4
	v_exp_f32_e32 v0, v0
	s_nop 0
	v_add_f32_e32 v0, 1.0, v0
	v_rcp_f32_e32 v6, v0
	v_mul_f32_e32 v0, 0xbfb8aa3b, v5
	v_exp_f32_e32 v0, v0
	s_nop 0
	v_add_f32_e32 v0, 1.0, v0
	v_rcp_f32_e32 v7, v0
	s_nop 0
	v_mul_f32 v4, v6, v4
	v_mul_f32 v5, v7, v5
	v_lshlrev_b32_e32 v6, 16, v8
	v_mul_f32_e32 v0, 0xbfb8aa3b, v6
	v_exp_f32_e32 v0, v0
	v_and_b32_e32 v7, 0xffff0000, v8
	v_mul_f32 v4, v14, v4
	v_mul_f32 v5, v15, v5
	v_add_f32_e32 v0, 1.0, v0
	v_rcp_f32_e32 v8, v0
	v_mul_f32_e32 v0, 0xbfb8aa3b, v7
	v_exp_f32_e32 v0, v0
	v_cvt_pk_bf16_f32 v4, v4, v5
	s_nop 1
	v_permlane32_swap_b32_e32 v2, v4
	v_add_f32_e32 v0, 1.0, v0
	v_rcp_f32_e32 v9, v0
	s_nop 0
	v_mul_f32 v6, v8, v6
	v_mul_f32 v7, v9, v7
	s_nop 0
	v_mul_f32 v6, v16, v6
	v_mul_f32 v7, v17, v7
	s_nop 0
	v_cvt_pk_bf16_f32 v5, v6, v7
	s_nop 1
	v_permlane32_swap_b32_e32 v3, v5
	global_store_dwordx4 v[46:47], v[2:5], off offset:96

.LBB0_410:
	s_add_i32 s10, s25, s80
	v_add_u32_e32 v0, v235, v236
	v_cvt_f32_i32_e32 v0, v0
	s_cmp_lg_u32 s10, -2
	s_mov_b64 s[10:11], -1
	s_cbranch_scc0 .LBB0_412
	s_nop 4
	v_add_f32_e32 v2, 0, v96
	v_subrev_f32_e32 v3, s4, v97
	v_fma_f32 v6, s2, v196, v80
	v_fma_f32 v7, s3, v197, v81
	v_fma_f32 v8, s2, v152, v82
	v_fma_f32 v9, s3, v153, v83
	v_max_f32_e32 v4, v2, v6
	v_max_f32_e32 v5, v3, v7
	v_max3_f32 v10, v4, s82, v5
	v_fma_f32 v4, s2, v226, v98
	v_fma_f32 v5, s3, v227, v99
	v_fma_f32 v202, s2, v164, v88
	v_fma_f32 v203, s3, v165, v89
	v_max_f32_e32 v11, v4, v8
	v_max_f32_e32 v12, v5, v9
	v_max3_f32 v14, v10, v11, v12
	v_fma_f32 v10, s2, v154, v100
	v_fma_f32 v11, s3, v155, v101
	v_fma_f32 v12, s2, v156, v84
	v_fma_f32 v13, s3, v157, v85
	v_fma_f32 v204, s2, v166, v106
	v_fma_f32 v205, s3, v167, v107
	v_max_f32_e32 v15, v10, v12
	v_max_f32_e32 v144, v11, v13
	v_max3_f32 v146, v14, v15, v144
	v_fma_f32 v14, s2, v158, v102
	v_fma_f32 v15, s3, v159, v103
	v_fma_f32 v144, s2, v160, v86
	v_fma_f32 v145, s3, v161, v87
	v_fma_f32 v206, s2, v168, v90
	v_fma_f32 v207, s3, v169, v91
	v_max_f32_e32 v147, v14, v144
	v_max_f32_e32 v148, v15, v145
	v_max3_f32 v148, v146, v147, v148
	v_fma_f32 v146, s2, v162, v104
	v_fma_f32 v147, s3, v163, v105
	v_fma_f32 v208, s2, v170, v108
	v_fma_f32 v209, s3, v171, v109
	v_max_f32_e32 v149, v146, v202
	v_max_f32_e32 v150, v147, v203
	v_max3_f32 v148, v148, v149, v150
	v_max_f32_e32 v149, v204, v206
	v_max_f32_e32 v150, v205, v207
	v_fma_f32 v210, s2, v172, v92
	v_fma_f32 v211, s3, v173, v93
	v_max3_f32 v148, v148, v149, v150
	v_max_f32_e32 v149, v208, v210
	v_max_f32_e32 v150, v209, v211
	v_fma_f32 v212, s2, v174, v110
	v_fma_f32 v213, s3, v175, v111
	v_fma_f32 v214, s2, v176, v94
	v_fma_f32 v215, s3, v177, v95
	v_max3_f32 v148, v148, v149, v150
	v_max_f32_e32 v149, v212, v214
	v_max_f32_e32 v150, v213, v215
	v_max3_f32 v239, v148, v149, v150
	v_mul_f32_e32 v238, s4, v0
	s_mov_b64 s[10:11], 0
.LBB0_412:
	s_andn2_b64 vcc, exec, s[10:11]
	s_cbranch_vccnz .LBB0_414
	v_add_f32 v4, v0, s38
	v_add_f32 v5, v0, s39
	v_add_f32_e32 v3, -1.0, v0
	v_and_b32_e32 v2, 0x7fffffff, v0
	v_and_b32_e32 v3, 0x7fffffff, v3
	v_and_b32_e32 v5, 0x7fffffff, v5
	v_and_b32_e32 v4, 0x7fffffff, v4
	v_fma_f32 v2, s4, v2, v96
	v_fma_f32 v3, s5, v3, v97
	v_fma_f32 v6, s4, v4, v80
	v_fma_f32 v7, s5, v5, v81
	v_add_f32 v8, v0, s40
	v_add_f32 v9, v0, s41
	v_max_f32_e32 v4, v2, v6
	v_max_f32_e32 v5, v3, v7
	v_max3_f32 v10, v4, s82, v5
	v_add_f32 v4, v0, s36
	v_add_f32 v5, v0, s37
	v_and_b32_e32 v5, 0x7fffffff, v5
	v_and_b32_e32 v4, 0x7fffffff, v4
	v_and_b32_e32 v9, 0x7fffffff, v9
	v_and_b32_e32 v8, 0x7fffffff, v8
	v_fma_f32 v4, s4, v4, v98
	v_fma_f32 v5, s5, v5, v99
	v_fma_f32 v8, s4, v8, v82
	v_fma_f32 v9, s5, v9, v83
	v_mov_b32_e32 v238, 0
	v_max_f32_e32 v11, v4, v8
	v_max_f32_e32 v12, v5, v9
	v_max3_f32 v14, v10, v11, v12
	v_add_f32 v10, v0, s42
	v_add_f32 v11, v0, s43
	v_add_f32 v12, v0, s44
	v_add_f32 v13, v0, s45
	v_and_b32_e32 v11, 0x7fffffff, v11
	v_and_b32_e32 v10, 0x7fffffff, v10
	v_and_b32_e32 v13, 0x7fffffff, v13
	v_and_b32_e32 v12, 0x7fffffff, v12
	v_fma_f32 v10, s4, v10, v100
	v_fma_f32 v11, s5, v11, v101
	v_fma_f32 v12, s4, v12, v84
	v_fma_f32 v13, s5, v13, v85
	s_nop 0
	v_max_f32_e32 v15, v10, v12
	v_max_f32_e32 v80, v11, v13
	v_max3_f32 v82, v14, v15, v80
	v_add_f32 v14, v0, s46
	v_add_f32 v15, v0, s47
	v_add_f32 v80, v0, s48
	v_add_f32 v81, v0, s49
	v_and_b32_e32 v15, 0x7fffffff, v15
	v_and_b32_e32 v14, 0x7fffffff, v14
	v_and_b32_e32 v81, 0x7fffffff, v81
	v_and_b32_e32 v80, 0x7fffffff, v80
	v_fma_f32 v14, s4, v14, v102
	v_fma_f32 v15, s5, v15, v103
	v_fma_f32 v144, s4, v80, v86
	v_fma_f32 v145, s5, v81, v87
	s_nop 0
	v_max_f32_e32 v80, v14, v144
	v_max_f32_e32 v81, v15, v145
	v_max3_f32 v84, v82, v80, v81
	v_add_f32 v80, v0, s50
	v_add_f32 v81, v0, s51
	v_add_f32 v82, v0, s52
	v_add_f32 v83, v0, s53
	v_and_b32_e32 v81, 0x7fffffff, v81
	v_and_b32_e32 v80, 0x7fffffff, v80
	v_fma_f32 v146, s4, v80, v104
	v_fma_f32 v147, s5, v81, v105
	v_and_b32_e32 v81, 0x7fffffff, v83
	v_and_b32_e32 v80, 0x7fffffff, v82
	v_fma_f32 v202, s4, v80, v88
	v_fma_f32 v203, s5, v81, v89
	v_add_f32 v82, v0, s58
	v_add_f32 v83, v0, s59
	v_max_f32_e32 v80, v146, v202
	v_max_f32_e32 v81, v147, v203
	v_max3_f32 v84, v84, v80, v81
	v_add_f32 v80, v0, s54
	v_add_f32 v81, v0, s55
	v_and_b32_e32 v81, 0x7fffffff, v81
	v_and_b32_e32 v80, 0x7fffffff, v80
	v_fma_f32 v204, s4, v80, v106
	v_fma_f32 v205, s5, v81, v107
	v_and_b32_e32 v81, 0x7fffffff, v83
	v_and_b32_e32 v80, 0x7fffffff, v82
	v_fma_f32 v206, s4, v80, v90
	v_fma_f32 v207, s5, v81, v91
	v_add_f32 v82, v0, s62
	v_add_f32 v83, v0, s63
	v_max_f32_e32 v80, v204, v206
	v_max_f32_e32 v81, v205, v207
	v_max3_f32 v84, v84, v80, v81
	v_add_f32 v80, v0, s60
	v_add_f32 v81, v0, s61
	v_and_b32_e32 v81, 0x7fffffff, v81
	v_and_b32_e32 v80, 0x7fffffff, v80
	v_fma_f32 v208, s4, v80, v108
	v_fma_f32 v209, s5, v81, v109
	v_and_b32_e32 v81, 0x7fffffff, v83
	v_and_b32_e32 v80, 0x7fffffff, v82
	v_fma_f32 v210, s4, v80, v92
	v_fma_f32 v211, s5, v81, v93
	v_add_f32 v82, v0, s66
	v_add_f32 v83, v0, s67
	v_max_f32_e32 v80, v208, v210
	v_max_f32_e32 v81, v209, v211
	v_max3_f32 v84, v84, v80, v81
	v_add_f32 v80, v0, s64
	v_add_f32 v81, v0, s65
	v_and_b32_e32 v81, 0x7fffffff, v81
	v_and_b32_e32 v80, 0x7fffffff, v80
	v_fma_f32 v212, s4, v80, v110
	v_fma_f32 v213, s5, v81, v111
	v_and_b32_e32 v81, 0x7fffffff, v83
	v_and_b32_e32 v80, 0x7fffffff, v82
	v_fma_f32 v214, s4, v80, v94
	v_fma_f32 v215, s5, v81, v95
	s_nop 0
	v_max_f32_e32 v0, v212, v214
	v_max_f32_e32 v80, v213, v215
	v_max3_f32 v239, v84, v0, v80
.LBB0_414:
	v_mov_b32_e32 v0, v239
	s_nop 1
	v_permlane32_swap_b32_e32 v239, v0
	v_max_f32_e32 v0, v0, v0
	v_max_f32_e32 v80, v239, v239
	v_max_f32_e32 v0, v80, v0
	v_add_f32_e32 v0, v238, v0
	v_mul_f32_e32 v0, 0x3e38aa3b, v0
	v_add_f32_e32 v80, 0x41000000, v237
	v_cmp_gt_f32_e32 vcc, v0, v80
	s_cbranch_vccz .LBB0_416
	v_max_f32_e32 v0, v0, v0
	v_max_f32_e32 v80, v237, v237
	v_max_f32_e32 v80, v80, v0
	v_sub_f32_e32 v0, v237, v80
	v_exp_f32_e32 v0, v0
	v_mov_b32_e32 v237, v80
	v_mul_f32_e32 v217, v217, v0
	v_mul_f32 v78, v78, v0
	v_mul_f32 v79, v79, v0
	v_mul_f32 v76, v76, v0
	v_mul_f32 v77, v77, v0
	v_mul_f32 v74, v74, v0
	v_mul_f32 v75, v75, v0
	v_mul_f32 v72, v72, v0
	v_mul_f32 v73, v73, v0
	v_mul_f32 v70, v70, v0
	v_mul_f32 v71, v71, v0
	v_mul_f32 v68, v68, v0
	v_mul_f32 v69, v69, v0
	v_mul_f32 v66, v66, v0
	v_mul_f32 v67, v67, v0
	v_mul_f32 v64, v64, v0
	v_mul_f32 v65, v65, v0
	v_mul_f32 v62, v62, v0
	v_mul_f32 v63, v63, v0
	v_mul_f32 v60, v60, v0
	v_mul_f32 v61, v61, v0
	v_mul_f32 v58, v58, v0
	v_mul_f32 v59, v59, v0
	v_mul_f32 v56, v56, v0
	v_mul_f32 v57, v57, v0
	v_mul_f32 v54, v54, v0
	v_mul_f32 v55, v55, v0
	v_mul_f32 v52, v52, v0
	v_mul_f32 v53, v53, v0
	v_mul_f32 v50, v50, v0
	v_mul_f32 v51, v51, v0
	v_mul_f32 v48, v48, v0
	v_mul_f32 v49, v49, v0
	v_mul_f32 v46, v46, v0
	v_mul_f32 v47, v47, v0
	v_mul_f32 v44, v44, v0
	v_mul_f32 v45, v45, v0
	v_mul_f32 v42, v42, v0
	v_mul_f32 v43, v43, v0
	v_mul_f32 v40, v40, v0
	v_mul_f32 v41, v41, v0
	v_mul_f32 v38, v38, v0
	v_mul_f32 v39, v39, v0
	v_mul_f32 v36, v36, v0
	v_mul_f32 v37, v37, v0
	v_mul_f32 v34, v34, v0
	v_mul_f32 v35, v35, v0
	v_mul_f32 v32, v32, v0
	v_mul_f32 v33, v33, v0
	v_mul_f32 v30, v30, v0
	v_mul_f32 v31, v31, v0
	v_mul_f32 v28, v28, v0
	v_mul_f32 v29, v29, v0
	v_mul_f32 v26, v26, v0
	v_mul_f32 v27, v27, v0
	v_mul_f32 v24, v24, v0
	v_mul_f32 v25, v25, v0
	v_mul_f32 v22, v22, v0
	v_mul_f32 v23, v23, v0
	v_mul_f32 v20, v20, v0
	v_mul_f32 v21, v21, v0
	v_mul_f32 v18, v18, v0
	v_mul_f32 v19, v19, v0
	v_mul_f32 v16, v16, v0
	v_mul_f32 v17, v17, v0
.LBB0_416:
	v_fma_f32 v95, v238, s83, -v237
	v_fmamk_f32 v0, v2, 0x3e38aa3b, v95
	v_exp_f32_e32 v98, v0
	v_fmamk_f32 v0, v6, 0x3e38aa3b, v95
	v_exp_f32_e32 v99, v0
	v_fmamk_f32 v0, v3, 0x3e38aa3b, v95
	v_exp_f32_e32 v2, v0
	v_fmamk_f32 v0, v7, 0x3e38aa3b, v95
	v_exp_f32_e32 v0, v0
	v_add_f32_e32 v3, v98, v99
	s_mov_b64 s[10:11], -1
	v_add_f32 v6, v2, v0
	v_add_f32 v7, v3, v1
	v_fmamk_f32 v3, v4, 0x3e38aa3b, v95
	v_fmamk_f32 v4, v8, 0x3e38aa3b, v95
	v_add_f32 v80, v6, v6
	v_add_f32 v81, v6, v7
	v_exp_f32_e32 v3, v3
	v_exp_f32_e32 v100, v4
	v_fmamk_f32 v4, v5, 0x3e38aa3b, v95
	v_fmamk_f32 v5, v9, 0x3e38aa3b, v95
	v_exp_f32_e32 v4, v4
	v_exp_f32_e32 v80, v5
	v_add_f32_e32 v5, v3, v100
	v_add_f32 v6, v4, v80
	v_add_f32 v7, v5, v81
	s_nop 0
	v_add_f32 v8, v6, v6
	v_add_f32 v9, v6, v7
	v_fmamk_f32 v5, v10, 0x3e38aa3b, v95
	v_fmamk_f32 v6, v12, 0x3e38aa3b, v95
	v_exp_f32_e32 v5, v5
	v_exp_f32_e32 v81, v6
	v_fmamk_f32 v6, v11, 0x3e38aa3b, v95
	v_fmamk_f32 v7, v13, 0x3e38aa3b, v95
	v_exp_f32_e32 v6, v6
	v_exp_f32_e32 v8, v7
	v_add_f32_e32 v7, v5, v81
	v_add_f32 v10, v6, v8
	v_add_f32 v11, v7, v9
	v_fmamk_f32 v7, v14, 0x3e38aa3b, v95
	v_fmamk_f32 v9, v144, 0x3e38aa3b, v95
	v_add_f32 v82, v10, v10
	v_add_f32 v83, v10, v11
	v_exp_f32_e32 v7, v7
	v_exp_f32_e32 v9, v9
	v_fmamk_f32 v10, v15, 0x3e38aa3b, v95
	v_fmamk_f32 v11, v145, 0x3e38aa3b, v95
	v_exp_f32_e32 v10, v10
	v_exp_f32_e32 v82, v11
	v_add_f32_e32 v11, v7, v9
	v_cvt_pk_bf16_f32 v144, v98, v2
	v_cvt_pk_bf16_f32 v145, v3, v4
	v_add_f32 v12, v10, v82
	v_add_f32 v13, v11, v83
	v_fmamk_f32 v11, v146, 0x3e38aa3b, v95
	v_add_f32 v14, v12, v12
	v_add_f32 v15, v12, v13
	v_fmamk_f32 v12, v202, 0x3e38aa3b, v95
	v_exp_f32_e32 v11, v11
	v_exp_f32_e32 v83, v12
	v_fmamk_f32 v12, v147, 0x3e38aa3b, v95
	v_fmamk_f32 v13, v203, 0x3e38aa3b, v95
	v_exp_f32_e32 v12, v12
	v_exp_f32_e32 v14, v13
	v_add_f32_e32 v13, v11, v83
	v_cvt_pk_bf16_f32 v146, v5, v6
	v_cvt_pk_bf16_f32 v147, v7, v10
	v_add_f32 v84, v12, v14
	v_add_f32 v85, v13, v15
	v_fmamk_f32 v13, v204, 0x3e38aa3b, v95
	v_add_f32 v85, v84, v85
	v_add_f32 v84, v84, v84
	v_fmamk_f32 v15, v206, 0x3e38aa3b, v95
	v_fmamk_f32 v84, v205, 0x3e38aa3b, v95
	v_exp_f32_e32 v13, v13
	v_exp_f32_e32 v15, v15
	v_exp_f32_e32 v86, v84
	v_fmamk_f32 v84, v207, 0x3e38aa3b, v95
	v_exp_f32_e32 v84, v84
	v_add_f32_e32 v87, v13, v15
	v_cvt_pk_bf16_f32 v10, v11, v12
	v_cvt_pk_bf16_f32 v11, v13, v86
	v_add_f32 v88, v86, v84
	v_add_f32 v89, v87, v85
	v_fmamk_f32 v85, v208, 0x3e38aa3b, v95
	v_add_f32 v89, v88, v89
	v_add_f32 v88, v88, v88
	v_fmamk_f32 v87, v210, 0x3e38aa3b, v95
	v_fmamk_f32 v88, v209, 0x3e38aa3b, v95
	v_exp_f32_e32 v85, v85
	v_exp_f32_e32 v87, v87
	v_exp_f32_e32 v90, v88
	v_fmamk_f32 v88, v211, 0x3e38aa3b, v95
	v_exp_f32_e32 v88, v88
	v_add_f32_e32 v91, v85, v87
	v_cvt_pk_bf16_f32 v12, v85, v90
	v_cvt_pk_bf16_f32 v6, v99, v0
	v_add_f32 v92, v90, v88
	v_add_f32 v93, v91, v89
	v_fmamk_f32 v89, v212, 0x3e38aa3b, v95
	v_add_f32 v93, v92, v93
	v_add_f32 v92, v92, v92
	v_fmamk_f32 v91, v214, 0x3e38aa3b, v95
	v_exp_f32_e32 v89, v89
	v_exp_f32_e32 v91, v91
	v_fmamk_f32 v92, v213, 0x3e38aa3b, v95
	v_fmac_f32_e32 v95, 0x3e38aa3b, v215
	v_exp_f32_e32 v94, v92
	v_exp_f32_e32 v92, v95
	v_add_f32_e32 v95, v89, v91
	v_cvt_pk_bf16_f32 v7, v100, v80
	v_cvt_pk_bf16_f32 v13, v89, v94
	v_add_f32 v96, v94, v92
	v_add_f32 v97, v95, v93
	v_cvt_pk_bf16_f32 v8, v81, v8
	v_add_f32_e32 v93, v96, v97
	v_add_f32_e32 v217, v217, v93
	v_cvt_pk_bf16_f32 v9, v9, v82
	v_cvt_pk_bf16_f32 v2, v83, v14
	v_cvt_pk_bf16_f32 v3, v15, v84
	v_cvt_pk_bf16_f32 v4, v87, v88
	v_cvt_pk_bf16_f32 v5, v91, v92

.LBB0_437:
	s_mov_b32 s97, s96
	s_waitcnt lgkmcnt(0)
	v_cmp_eq_u64_e32 vcc, s[96:97], v[2:3]
	s_nop 1
	v_cndmask_b32_e64 v0, 0, 1, vcc
	s_nop 0
	v_readfirstlane_b32 s8, v0
	s_bitcmp1_b32 s8, 0
	s_cselect_b64 s[8:9], -1, 0
	s_and_b64 vcc, exec, s[8:9]
	s_cbranch_vccnz .LBB0_449
	s_cmp_gt_i32 s15, s21
	s_cbranch_scc1 .LBB0_446
	s_add_i32 s8, s13, 0xffff4000
	s_and_b32 s8, s8, 0xc000
	v_add_u32_e32 v0, s8, v221
	v_add_u32_e32 v6, v0, v222
	v_add_u32_e32 v14, v0, v223
	ds_read_b128 v[2:5], v6
	ds_read_b128 v[6:9], v6 offset:4096
	ds_read_b128 v[10:13], v14
	ds_read_b128 v[128:131], v14 offset:4096
	v_add_u32_e32 v14, v0, v224
	v_add_u32_e32 v0, v0, v219
	ds_read_b128 v[132:135], v14
	ds_read_b128 v[136:139], v14 offset:4096
	ds_read_b128 v[144:147], v0
	ds_read_b128 v[148:151], v0 offset:4096
	s_add_i32 s8, s12, s10
	s_lshl_b32 s9, s14, 14
	s_waitcnt lgkmcnt(7)
	v_mfma_f32_32x32x16_bf16 v[96:111], v[2:5], v[112:115], 0
	v_add_u32_e32 v235, s9, v220
	s_waitcnt lgkmcnt(6)
	v_mfma_f32_32x32x16_bf16 v[80:95], v[6:9], v[112:115], 0
	s_waitcnt lgkmcnt(5)
	v_mfma_f32_32x32x16_bf16 v[96:111], v[10:13], v[116:119], v[96:111]
	s_waitcnt lgkmcnt(4)
	v_mfma_f32_32x32x16_bf16 v[80:95], v[128:131], v[116:119], v[80:95]
	ds_read_b64_tr_b16 v[6:7], v235
	ds_read_b64_tr_b16 v[8:9], v235 offset:512
	ds_read_b64_tr_b16 v[2:3], v235 offset:1024
	ds_read_b64_tr_b16 v[4:5], v235 offset:1536
	ds_read_b64_tr_b16 v[140:141], v235 offset:4096
	ds_read_b64_tr_b16 v[142:143], v235 offset:4608
	ds_read_b64_tr_b16 v[128:129], v235 offset:5120
	ds_read_b64_tr_b16 v[130:131], v235 offset:5632
	s_waitcnt lgkmcnt(11)
	v_mfma_f32_32x32x16_bf16 v[96:111], v[132:135], v[120:123], v[96:111]
	s_waitcnt lgkmcnt(10)
	v_mfma_f32_32x32x16_bf16 v[80:95], v[136:139], v[120:123], v[80:95]
	s_waitcnt lgkmcnt(9)
	v_mfma_f32_32x32x16_bf16 v[96:111], v[144:147], v[124:127], v[96:111]
	ds_read_b64_tr_b16 v[136:137], v235 offset:2048
	ds_read_b64_tr_b16 v[138:139], v235 offset:2560
	ds_read_b64_tr_b16 v[10:11], v235 offset:3072
	ds_read_b64_tr_b16 v[12:13], v235 offset:3584
	ds_read_b64_tr_b16 v[144:145], v235 offset:6144
	ds_read_b64_tr_b16 v[146:147], v235 offset:6656
	ds_read_b64_tr_b16 v[132:133], v235 offset:7168
	ds_read_b64_tr_b16 v[134:135], v235 offset:7680
	s_waitcnt lgkmcnt(14)
	v_mfma_f32_32x32x16_bf16 v[80:95], v[148:151], v[124:127], v[80:95]
	v_add_u32_e32 v0, v233, v218
	v_cvt_f32_i32_e32 v0, v0
	s_cmp_lg_u32 s8, 1
	s_mov_b64 s[8:9], -1
	s_cbranch_scc0 .LBB0_441
	v_add_f32_e32 v14, 0, v96
	v_subrev_f32_e32 v15, s4, v97
	s_nop 4
	v_fma_f32 v186, s2, v196, v80
	v_fma_f32 v187, s3, v197, v81
	v_fma_f32 v184, s2, v226, v98
	v_fma_f32 v185, s3, v227, v99
	v_max_f32_e32 v148, v14, v186
	v_max_f32_e32 v149, v15, v187
	v_fma_f32 v188, s2, v152, v82
	v_fma_f32 v189, s3, v153, v83
	v_max3_f32 v148, v148, s82, v149
	v_max_f32_e32 v149, v184, v188
	v_max_f32_e32 v150, v185, v189
	v_fma_f32 v190, s2, v154, v100
	v_fma_f32 v191, s3, v155, v101
	v_fma_f32 v192, s2, v156, v84
	v_fma_f32 v193, s3, v157, v85
	v_max3_f32 v148, v148, v149, v150
	v_max_f32_e32 v149, v190, v192
	v_max_f32_e32 v150, v191, v193
	v_fma_f32 v194, s2, v158, v102
	v_fma_f32 v195, s3, v159, v103
	v_fma_f32 v198, s2, v160, v86
	v_fma_f32 v199, s3, v161, v87
	v_max3_f32 v148, v148, v149, v150
	v_max_f32_e32 v149, v194, v198
	v_max_f32_e32 v150, v195, v199
	v_fma_f32 v200, s2, v162, v104
	v_fma_f32 v201, s3, v163, v105
	v_fma_f32 v202, s2, v164, v88
	v_fma_f32 v203, s3, v165, v89
	v_max3_f32 v148, v148, v149, v150
	v_max_f32_e32 v149, v200, v202
	v_max_f32_e32 v150, v201, v203
	v_fma_f32 v204, s2, v166, v106
	v_fma_f32 v205, s3, v167, v107
	v_fma_f32 v206, s2, v168, v90
	v_fma_f32 v207, s3, v169, v91
	v_max3_f32 v148, v148, v149, v150
	v_max_f32_e32 v149, v204, v206
	v_max_f32_e32 v150, v205, v207
	v_fma_f32 v208, s2, v170, v108
	v_fma_f32 v209, s3, v171, v109
	v_fma_f32 v210, s2, v172, v92
	v_fma_f32 v211, s3, v173, v93
	v_max3_f32 v148, v148, v149, v150
	v_max_f32_e32 v149, v208, v210
	v_max_f32_e32 v150, v209, v211
	v_fma_f32 v212, s2, v174, v110
	v_fma_f32 v213, s3, v175, v111
	v_fma_f32 v214, s2, v176, v94
	v_fma_f32 v215, s3, v177, v95
	v_max3_f32 v148, v148, v149, v150
	v_max_f32_e32 v149, v212, v214
	v_max_f32_e32 v150, v213, v215
	v_max3_f32 v237, v148, v149, v150
	v_mul_f32_e32 v236, s4, v0
	s_mov_b64 s[8:9], 0
.LBB0_441:
	s_andn2_b64 vcc, exec, s[8:9]
	s_cbranch_vccnz .LBB0_443
	v_add_f32_e32 v15, -1.0, v0
	v_add_f32 v148, v0, s38
	v_add_f32 v149, v0, s39
	v_and_b32_e32 v14, 0x7fffffff, v0
	v_and_b32_e32 v15, 0x7fffffff, v15
	v_fma_f32 v14, s4, v14, v96
	v_fma_f32 v15, s5, v15, v97
	v_and_b32_e32 v97, 0x7fffffff, v149
	v_and_b32_e32 v96, 0x7fffffff, v148
	v_fma_f32 v186, s4, v96, v80
	v_fma_f32 v187, s5, v97, v81
	v_add_f32 v96, v0, s40
	v_add_f32 v97, v0, s41
	v_max_f32_e32 v80, v14, v186
	v_max_f32_e32 v81, v15, v187
	v_max3_f32 v148, v80, s82, v81
	v_add_f32 v80, v0, s36
	v_add_f32 v81, v0, s37
	v_and_b32_e32 v81, 0x7fffffff, v81
	v_and_b32_e32 v80, 0x7fffffff, v80
	v_fma_f32 v184, s4, v80, v98
	v_fma_f32 v185, s5, v81, v99
	v_and_b32_e32 v81, 0x7fffffff, v97
	v_and_b32_e32 v80, 0x7fffffff, v96
	v_fma_f32 v188, s4, v80, v82
	v_fma_f32 v189, s5, v81, v83
	v_add_f32 v82, v0, s44
	v_add_f32 v83, v0, s45
	v_max_f32_e32 v80, v184, v188
	v_max_f32_e32 v81, v185, v189
	v_max3_f32 v96, v148, v80, v81
	v_add_f32 v80, v0, s42
	v_add_f32 v81, v0, s43
	v_and_b32_e32 v81, 0x7fffffff, v81
	v_and_b32_e32 v80, 0x7fffffff, v80
	v_fma_f32 v190, s4, v80, v100
	v_fma_f32 v191, s5, v81, v101
	v_and_b32_e32 v81, 0x7fffffff, v83
	v_and_b32_e32 v80, 0x7fffffff, v82
	v_fma_f32 v192, s4, v80, v84
	v_fma_f32 v193, s5, v81, v85
	v_add_f32 v82, v0, s48
	v_add_f32 v83, v0, s49
	v_max_f32_e32 v80, v190, v192
	v_max_f32_e32 v81, v191, v193
	v_max3_f32 v84, v96, v80, v81
	v_add_f32 v80, v0, s46
	v_add_f32 v81, v0, s47
	v_and_b32_e32 v81, 0x7fffffff, v81
	v_and_b32_e32 v80, 0x7fffffff, v80
	v_fma_f32 v194, s4, v80, v102
	v_fma_f32 v195, s5, v81, v103
	v_and_b32_e32 v81, 0x7fffffff, v83
	v_and_b32_e32 v80, 0x7fffffff, v82
	v_fma_f32 v198, s4, v80, v86
	v_fma_f32 v199, s5, v81, v87
	v_add_f32 v82, v0, s52
	v_add_f32 v83, v0, s53
	v_max_f32_e32 v80, v194, v198
	v_max_f32_e32 v81, v195, v199
	v_max3_f32 v84, v84, v80, v81
	v_add_f32 v80, v0, s50
	v_add_f32 v81, v0, s51
	v_and_b32_e32 v81, 0x7fffffff, v81
	v_and_b32_e32 v80, 0x7fffffff, v80
	v_fma_f32 v200, s4, v80, v104
	v_fma_f32 v201, s5, v81, v105
	v_and_b32_e32 v81, 0x7fffffff, v83
	v_and_b32_e32 v80, 0x7fffffff, v82
	v_fma_f32 v202, s4, v80, v88
	v_fma_f32 v203, s5, v81, v89
	v_add_f32 v82, v0, s58
	v_add_f32 v83, v0, s59
	v_max_f32_e32 v80, v200, v202
	v_max_f32_e32 v81, v201, v203
	v_max3_f32 v84, v84, v80, v81
	v_add_f32 v80, v0, s54
	v_add_f32 v81, v0, s55
	v_and_b32_e32 v81, 0x7fffffff, v81
	v_and_b32_e32 v80, 0x7fffffff, v80
	v_fma_f32 v204, s4, v80, v106
	v_fma_f32 v205, s5, v81, v107
	v_and_b32_e32 v81, 0x7fffffff, v83
	v_and_b32_e32 v80, 0x7fffffff, v82
	v_fma_f32 v206, s4, v80, v90
	v_fma_f32 v207, s5, v81, v91
	v_add_f32 v82, v0, s62
	v_add_f32 v83, v0, s63
	v_max_f32_e32 v80, v204, v206
	v_max_f32_e32 v81, v205, v207
	v_max3_f32 v84, v84, v80, v81
	v_add_f32 v80, v0, s60
	v_add_f32 v81, v0, s61
	v_and_b32_e32 v81, 0x7fffffff, v81
	v_and_b32_e32 v80, 0x7fffffff, v80
	v_fma_f32 v208, s4, v80, v108
	v_fma_f32 v209, s5, v81, v109
	v_and_b32_e32 v81, 0x7fffffff, v83
	v_and_b32_e32 v80, 0x7fffffff, v82
	v_fma_f32 v210, s4, v80, v92
	v_fma_f32 v211, s5, v81, v93
	v_add_f32 v82, v0, s66
	v_add_f32 v83, v0, s67
	v_max_f32_e32 v80, v208, v210
	v_max_f32_e32 v81, v209, v211
	v_max3_f32 v84, v84, v80, v81
	v_add_f32 v80, v0, s64
	v_add_f32 v81, v0, s65
	v_and_b32_e32 v81, 0x7fffffff, v81
	v_and_b32_e32 v80, 0x7fffffff, v80
	v_fma_f32 v212, s4, v80, v110
	v_fma_f32 v213, s5, v81, v111
	v_and_b32_e32 v81, 0x7fffffff, v83
	v_and_b32_e32 v80, 0x7fffffff, v82
	v_fma_f32 v214, s4, v80, v94
	v_fma_f32 v215, s5, v81, v95
	v_mov_b32_e32 v236, 0
	v_max_f32_e32 v0, v212, v214
	v_max_f32_e32 v80, v213, v215
	v_max3_f32 v237, v84, v0, v80
.LBB0_443:
	v_mov_b32_e32 v0, v237
	s_nop 1
	v_permlane32_swap_b32_e32 v237, v0
	v_max_f32_e32 v0, v0, v0
	v_max_f32_e32 v80, v237, v237
	v_max_f32_e32 v0, v80, v0
	v_add_f32_e32 v0, v236, v0
	v_mul_f32_e32 v0, 0x3e38aa3b, v0
	v_add_f32_e32 v80, 0x41000000, v234
	v_cmp_gt_f32_e32 vcc, v0, v80
	s_cbranch_vccz .LBB0_445
	v_max_f32_e32 v0, v0, v0
	v_max_f32_e32 v80, v234, v234
	v_max_f32_e32 v80, v80, v0
	v_sub_f32_e32 v0, v234, v80
	v_exp_f32_e32 v0, v0
	v_mov_b32_e32 v234, v80
	v_mul_f32_e32 v217, v217, v0
	v_mul_f32 v78, v78, v0
	v_mul_f32 v79, v79, v0
	v_mul_f32 v76, v76, v0
	v_mul_f32 v77, v77, v0
	v_mul_f32 v74, v74, v0
	v_mul_f32 v75, v75, v0
	v_mul_f32 v72, v72, v0
	v_mul_f32 v73, v73, v0
	v_mul_f32 v70, v70, v0
	v_mul_f32 v71, v71, v0
	v_mul_f32 v68, v68, v0
	v_mul_f32 v69, v69, v0
	v_mul_f32 v66, v66, v0
	v_mul_f32 v67, v67, v0
	v_mul_f32 v64, v64, v0
	v_mul_f32 v65, v65, v0
	v_mul_f32 v62, v62, v0
	v_mul_f32 v63, v63, v0
	v_mul_f32 v60, v60, v0
	v_mul_f32 v61, v61, v0
	v_mul_f32 v58, v58, v0
	v_mul_f32 v59, v59, v0
	v_mul_f32 v56, v56, v0
	v_mul_f32 v57, v57, v0
	v_mul_f32 v54, v54, v0
	v_mul_f32 v55, v55, v0
	v_mul_f32 v52, v52, v0
	v_mul_f32 v53, v53, v0
	v_mul_f32 v50, v50, v0
	v_mul_f32 v51, v51, v0
	v_mul_f32 v48, v48, v0
	v_mul_f32 v49, v49, v0
	v_mul_f32 v46, v46, v0
	v_mul_f32 v47, v47, v0
	v_mul_f32 v44, v44, v0
	v_mul_f32 v45, v45, v0
	v_mul_f32 v42, v42, v0
	v_mul_f32 v43, v43, v0
	v_mul_f32 v40, v40, v0
	v_mul_f32 v41, v41, v0
	v_mul_f32 v38, v38, v0
	v_mul_f32 v39, v39, v0
	v_mul_f32 v36, v36, v0
	v_mul_f32 v37, v37, v0
	v_mul_f32 v34, v34, v0
	v_mul_f32 v35, v35, v0
	v_mul_f32 v32, v32, v0
	v_mul_f32 v33, v33, v0
	v_mul_f32 v30, v30, v0
	v_mul_f32 v31, v31, v0
	v_mul_f32 v28, v28, v0
	v_mul_f32 v29, v29, v0
	v_mul_f32 v26, v26, v0
	v_mul_f32 v27, v27, v0
	v_mul_f32 v24, v24, v0
	v_mul_f32 v25, v25, v0
	v_mul_f32 v22, v22, v0
	v_mul_f32 v23, v23, v0
	v_mul_f32 v20, v20, v0
	v_mul_f32 v21, v21, v0
	v_mul_f32 v18, v18, v0
	v_mul_f32 v19, v19, v0
	v_mul_f32 v16, v16, v0
	v_mul_f32 v17, v17, v0
.LBB0_445:
	v_fma_f32 v109, v236, s83, -v234
	v_fmamk_f32 v0, v14, 0x3e38aa3b, v109
	v_exp_f32_e32 v110, v0
	v_fmamk_f32 v0, v186, 0x3e38aa3b, v109
	v_exp_f32_e32 v111, v0
	v_fmamk_f32 v0, v15, 0x3e38aa3b, v109
	v_exp_f32_e32 v14, v0
	v_fmamk_f32 v0, v187, 0x3e38aa3b, v109
	v_exp_f32_e32 v0, v0
	v_add_f32_e32 v15, v110, v111
	v_add_f32 v80, v14, v0
	v_add_f32 v81, v15, v1
	s_nop 0
	v_add_f32 v90, v80, v80
	v_add_f32 v91, v80, v81
	v_fmamk_f32 v80, v188, 0x3e38aa3b, v109
	v_fmamk_f32 v15, v184, 0x3e38aa3b, v109
	v_exp_f32_e32 v148, v80
	v_fmamk_f32 v80, v185, 0x3e38aa3b, v109
	v_exp_f32_e32 v15, v15
	v_exp_f32_e32 v82, v80
	v_fmamk_f32 v80, v189, 0x3e38aa3b, v109
	v_exp_f32_e32 v90, v80
	v_add_f32_e32 v83, v15, v148
	v_add_f32 v80, v82, v90
	v_add_f32 v81, v83, v91
	s_nop 0
	v_add_f32 v92, v80, v80
	v_add_f32 v93, v80, v81
	v_fmamk_f32 v80, v190, 0x3e38aa3b, v109
	v_exp_f32_e32 v83, v80
	v_fmamk_f32 v80, v192, 0x3e38aa3b, v109
	v_exp_f32_e32 v91, v80
	v_fmamk_f32 v80, v191, 0x3e38aa3b, v109
	v_exp_f32_e32 v84, v80
	v_fmamk_f32 v80, v193, 0x3e38aa3b, v109
	v_exp_f32_e32 v92, v80
	v_add_f32_e32 v85, v83, v91
	v_add_f32 v80, v84, v92
	v_add_f32 v81, v85, v93
	s_nop 0
	v_add_f32 v94, v80, v80
	v_add_f32 v95, v80, v81
	v_fmamk_f32 v80, v194, 0x3e38aa3b, v109
	v_exp_f32_e32 v85, v80
	v_fmamk_f32 v80, v198, 0x3e38aa3b, v109
	v_exp_f32_e32 v93, v80
	v_fmamk_f32 v80, v195, 0x3e38aa3b, v109
	v_exp_f32_e32 v86, v80
	v_fmamk_f32 v80, v199, 0x3e38aa3b, v109
	v_exp_f32_e32 v94, v80
	v_add_f32_e32 v87, v85, v93
	v_add_f32 v80, v86, v94
	v_add_f32 v81, v87, v95
	s_nop 0
	v_add_f32 v96, v80, v80
	v_add_f32 v97, v80, v81
	v_fmamk_f32 v80, v200, 0x3e38aa3b, v109
	v_exp_f32_e32 v87, v80
	v_fmamk_f32 v80, v202, 0x3e38aa3b, v109
	v_exp_f32_e32 v95, v80
	v_fmamk_f32 v80, v201, 0x3e38aa3b, v109
	v_exp_f32_e32 v88, v80
	v_fmamk_f32 v80, v203, 0x3e38aa3b, v109
	v_exp_f32_e32 v96, v80
	v_add_f32_e32 v89, v87, v95
	v_add_f32 v80, v88, v96
	v_add_f32 v81, v89, v97
	s_nop 0
	v_add_f32 v98, v80, v80
	v_add_f32 v99, v80, v81
	v_fmamk_f32 v80, v204, 0x3e38aa3b, v109
	v_exp_f32_e32 v89, v80
	v_fmamk_f32 v80, v206, 0x3e38aa3b, v109
	v_exp_f32_e32 v97, v80
	v_fmamk_f32 v80, v205, 0x3e38aa3b, v109
	v_exp_f32_e32 v100, v80
	v_fmamk_f32 v80, v207, 0x3e38aa3b, v109
	v_exp_f32_e32 v98, v80
	v_add_f32_e32 v101, v89, v97
	v_add_f32 v80, v100, v98
	v_add_f32 v81, v101, v99
	s_nop 0
	v_add_f32 v102, v80, v80
	v_add_f32 v103, v80, v81
	v_fmamk_f32 v80, v208, 0x3e38aa3b, v109
	v_exp_f32_e32 v99, v80
	v_fmamk_f32 v80, v210, 0x3e38aa3b, v109
	v_exp_f32_e32 v101, v80
	v_fmamk_f32 v80, v209, 0x3e38aa3b, v109
	v_exp_f32_e32 v104, v80
	v_fmamk_f32 v80, v211, 0x3e38aa3b, v109
	v_exp_f32_e32 v102, v80
	v_add_f32_e32 v105, v99, v101
	v_add_f32 v80, v104, v102
	v_add_f32 v81, v105, v103
	s_nop 0
	v_add_f32 v106, v80, v80
	v_add_f32 v107, v80, v81
	v_fmamk_f32 v80, v212, 0x3e38aa3b, v109
	v_exp_f32_e32 v103, v80
	v_fmamk_f32 v80, v214, 0x3e38aa3b, v109
	v_exp_f32_e32 v105, v80
	v_fmamk_f32 v80, v213, 0x3e38aa3b, v109
	v_fmac_f32_e32 v109, 0x3e38aa3b, v215
	v_exp_f32_e32 v108, v80
	v_exp_f32_e32 v106, v109
	v_add_f32_e32 v109, v103, v105
	v_add_f32 v80, v108, v106
	v_add_f32 v81, v109, v107
	s_nop 0
	v_add_f32_e32 v80, v80, v81
	v_add_f32_e32 v217, v217, v80
	v_cvt_pk_bf16_f32 v80, v110, v14
	v_cvt_pk_bf16_f32 v81, v15, v82
	v_cvt_pk_bf16_f32 v82, v83, v84
	v_cvt_pk_bf16_f32 v83, v85, v86
	v_cvt_pk_bf16_f32 v84, v87, v88
	v_cvt_pk_bf16_f32 v85, v89, v100
	v_cvt_pk_bf16_f32 v86, v99, v104
	v_cvt_pk_bf16_f32 v87, v103, v108
	v_cvt_pk_bf16_f32 v88, v111, v0
	v_cvt_pk_bf16_f32 v89, v148, v90
	v_cvt_pk_bf16_f32 v90, v91, v92
	v_cvt_pk_bf16_f32 v91, v93, v94
	v_cvt_pk_bf16_f32 v92, v95, v96
	v_cvt_pk_bf16_f32 v93, v97, v98
	v_cvt_pk_bf16_f32 v94, v101, v102
	v_cvt_pk_bf16_f32 v95, v105, v106
	v_mfma_f32_32x32x16_bf16 v[64:79], v[6:9], v[80:83], v[64:79]
	s_waitcnt lgkmcnt(12)
	v_mfma_f32_32x32x16_bf16 v[64:79], v[2:5], v[84:87], v[64:79]
	ds_read_b64_tr_b16 v[2:3], v235 offset:8192
	ds_read_b64_tr_b16 v[4:5], v235 offset:8704
	ds_read_b64_tr_b16 v[6:7], v235 offset:9216
	ds_read_b64_tr_b16 v[8:9], v235 offset:9728
	s_waitcnt lgkmcnt(10)
	v_mfma_f32_32x32x16_bf16 v[64:79], v[136:139], v[88:91], v[64:79]
	s_waitcnt lgkmcnt(8)
	v_mfma_f32_32x32x16_bf16 v[64:79], v[10:13], v[92:95], v[64:79]
	s_waitcnt lgkmcnt(2)
	v_mfma_f32_32x32x16_bf16 v[32:47], v[2:5], v[80:83], v[32:47]
	ds_read_b64_tr_b16 v[2:3], v235 offset:12288
	ds_read_b64_tr_b16 v[4:5], v235 offset:12800
	ds_read_b64_tr_b16 v[10:11], v235 offset:13312
	ds_read_b64_tr_b16 v[12:13], v235 offset:13824
	v_mfma_f32_32x32x16_bf16 v[48:63], v[140:143], v[80:83], v[48:63]
	s_waitcnt lgkmcnt(2)
	v_mfma_f32_32x32x16_bf16 v[16:31], v[2:5], v[80:83], v[16:31]
	v_mfma_f32_32x32x16_bf16 v[32:47], v[6:9], v[84:87], v[32:47]
	ds_read_b64_tr_b16 v[2:3], v235 offset:10240
	ds_read_b64_tr_b16 v[4:5], v235 offset:10752
	ds_read_b64_tr_b16 v[6:7], v235 offset:11264
	ds_read_b64_tr_b16 v[8:9], v235 offset:11776
	v_mfma_f32_32x32x16_bf16 v[48:63], v[128:131], v[84:87], v[48:63]
	s_waitcnt lgkmcnt(4)
	v_mfma_f32_32x32x16_bf16 v[16:31], v[10:13], v[84:87], v[16:31]
	s_waitcnt lgkmcnt(2)
	v_mfma_f32_32x32x16_bf16 v[32:47], v[2:5], v[88:91], v[32:47]
	ds_read_b64_tr_b16 v[2:3], v235 offset:14336
	ds_read_b64_tr_b16 v[4:5], v235 offset:14848
	ds_read_b64_tr_b16 v[10:11], v235 offset:15360
	ds_read_b64_tr_b16 v[12:13], v235 offset:15872
	v_mfma_f32_32x32x16_bf16 v[48:63], v[144:147], v[88:91], v[48:63]
	s_waitcnt lgkmcnt(2)
	v_mfma_f32_32x32x16_bf16 v[16:31], v[2:5], v[88:91], v[16:31]
	v_mfma_f32_32x32x16_bf16 v[48:63], v[132:135], v[92:95], v[48:63]
	v_mfma_f32_32x32x16_bf16 v[32:47], v[6:9], v[92:95], v[32:47]
	s_waitcnt lgkmcnt(0)
	v_mfma_f32_32x32x16_bf16 v[16:31], v[10:13], v[92:95], v[16:31]
